# streaming (nt) hint on read-once f32 weight / x loads in the prologue and in the late weight conversion (they ran through L1/L2 beside the GEMM tiles)
# speedup vs baseline: 1.3852x; 1.0350x over previous
.LBB0_24:
	v_add_u32_e32 v16, 0x400, v4
	v_lshrrev_b32_e32 v12, 3, v4
	v_add_u32_e32 v17, 0x400, v5
	v_lshrrev_b32_e32 v18, 3, v16
	v_lshrrev_b32_e32 v14, 3, v5
	v_lshlrev_b32_e32 v24, 2, v12
	v_mad_u64_u32 v[12:13], s[6:7], v12, s4, v[6:7]
	v_lshrrev_b32_e32 v20, 3, v17
	v_lshlrev_b32_e32 v26, 2, v18
	v_mad_u64_u32 v[18:19], s[6:7], v18, s4, v[6:7]
	v_lshlrev_b32_e32 v25, 2, v14
	v_mad_u64_u32 v[14:15], s[6:7], v14, s4, v[6:7]
	v_lshl_add_u64 v[12:13], v[12:13], 0, v[2:3]
	v_lshlrev_b32_e32 v27, 2, v20
	v_mad_u64_u32 v[20:21], s[6:7], v20, s4, v[6:7]
	v_lshl_add_u64 v[18:19], v[18:19], 0, v[2:3]
	v_add_co_u32_e32 v12, vcc, s5, v12
	v_add_co_u32_e64 v18, s[6:7], s5, v18
	v_lshl_add_u64 v[14:15], v[14:15], 0, v[2:3]
	v_lshl_add_u64 v[20:21], v[20:21], 0, v[2:3]
	v_addc_co_u32_e32 v13, vcc, 0, v13, vcc
	v_addc_co_u32_e64 v19, s[6:7], 0, v19, s[6:7]
	v_add_co_u32_e32 v14, vcc, s5, v14
	v_add_co_u32_e64 v20, s[6:7], s5, v20
	global_load_dword v16, v24, s[14:15]
	global_load_dword v17, v25, s[14:15]
	global_load_dword v22, v26, s[14:15]
	global_load_dword v23, v27, s[14:15]
	v_addc_co_u32_e64 v21, s[6:7], 0, v21, s[6:7]
	v_addc_co_u32_e32 v15, vcc, 0, v15, vcc
	global_load_dword v18, v[18:19], off nt
	s_nop 0
	global_load_dword v19, v[20:21], off nt
	s_nop 0
	global_load_dword v12, v[12:13], off nt
	s_nop 0
	global_load_dword v13, v[14:15], off nt
	v_add_u32_e32 v11, -2, v11
	v_cmp_eq_u32_e32 vcc, 0, v11
	v_add_u32_e32 v5, 0x800, v5
	v_add_u32_e32 v4, 0x800, v4
	v_add_u32_e32 v20, v9, v24
	s_or_b64 s[8:9], vcc, s[8:9]
	v_add_u32_e32 v21, v9, v25
	v_add_u32_e32 v24, v9, v26
	v_add_u32_e32 v25, v9, v27
	s_waitcnt vmcnt(2)
	v_pk_mul_f32 v[14:15], v[22:23], v[18:19]
	s_waitcnt vmcnt(0)
	v_pk_mul_f32 v[12:13], v[16:17], v[12:13]
	ds_write_b32 v20, v12
	ds_write_b32 v21, v13
	ds_write_b32 v24, v14
	ds_write_b32 v25, v15
	s_andn2_b64 exec, exec, s[8:9]
	s_cbranch_execnz .LBB0_24
	s_or_b64 exec, exec, s[8:9]
	v_and_b32_e32 v3, 2, v10
	v_cmp_eq_u32_e32 vcc, 0, v3
	s_and_saveexec_b64 s[6:7], vcc
	s_cbranch_execz .LBB0_27
	v_readlane_b32 s12, v233, 11
	v_readlane_b32 s16, v233, 15
	v_readlane_b32 s17, v233, 16
	v_lshrrev_b32_e32 v3, 3, v5
	v_lshrrev_b32_e32 v10, 3, v4
	s_movk_i32 s8, 0x3820
	v_mov_b64_e32 v[6:7], s[16:17]
	v_lshlrev_b32_e32 v12, 2, v10
	v_lshlrev_b32_e32 v13, 2, v3
	v_mad_u64_u32 v[10:11], s[4:5], v10, s8, v[6:7]
	v_mad_u64_u32 v[6:7], s[4:5], v3, s8, v[6:7]
	v_mov_b32_e32 v3, 0
	v_lshl_add_u64 v[10:11], v[10:11], 0, v[2:3]
	s_movk_i32 s4, 0x2000
	v_lshl_add_u64 v[2:3], v[6:7], 0, v[2:3]
	v_add_co_u32_e32 v6, vcc, s4, v10
	v_readlane_b32 s14, v233, 13
	s_nop 0
	v_addc_co_u32_e32 v7, vcc, 0, v11, vcc
	v_readlane_b32 s15, v233, 14
	v_add_co_u32_e32 v2, vcc, 0x2000, v2
	s_nop 3
	global_load_dword v4, v12, s[14:15]
	global_load_dword v5, v13, s[14:15]
	v_addc_co_u32_e32 v3, vcc, 0, v3, vcc
	global_load_dword v6, v[6:7], off nt
	s_nop 0
	global_load_dword v7, v[2:3], off nt
	v_add_u32_e32 v10, v9, v12
	v_readlane_b32 s13, v233, 12
	v_readlane_b32 s18, v233, 17
	v_readlane_b32 s19, v233, 18
	v_readlane_b32 s20, v233, 19
	v_readlane_b32 s21, v233, 20
	v_readlane_b32 s22, v233, 21
	v_readlane_b32 s23, v233, 22
	v_readlane_b32 s24, v233, 23
	v_readlane_b32 s25, v233, 24
	v_readlane_b32 s26, v233, 25
	v_readlane_b32 s27, v233, 26
	v_add_u32_e32 v9, v9, v13
	s_waitcnt vmcnt(0)
	v_pk_mul_f32 v[2:3], v[4:5], v[6:7]
	ds_write_b32 v10, v2
	ds_write_b32 v9, v3

.LBB0_29:
	global_load_dword v6, v[2:3], off nt
	global_load_dword v7, v[0:1], off nt
	v_add_u32_e32 v4, 0x200, v4
	v_cmp_lt_u32_e32 vcc, s4, v4
	v_lshl_add_u64 v[2:3], v[2:3], 0, s[46:47]
	v_lshl_add_u64 v[0:1], v[0:1], 0, s[52:53]
	s_or_b64 s[8:9], vcc, s[8:9]
	s_waitcnt vmcnt(0)
	v_mul_f32_e32 v6, v6, v7
	ds_write_b32 v5, v6
	v_add_u32_e32 v5, 0x100, v5
	s_andn2_b64 exec, exec, s[8:9]
	s_cbranch_execnz .LBB0_29
.LBB0_30:
	s_or_b64 exec, exec, s[6:7]
	s_lshl_b32 s4, s2, 3
	s_add_i32 s46, s44, s4
	s_waitcnt lgkmcnt(0)
	s_lshl_b32 s3, s3, 3
	v_readlane_b32 s8, v233, 11
	v_readlane_b32 s9, v233, 12
	s_nop 4
	v_lshlrev_b32_e32 v124, 4, v218
	s_lshl_b32 s6, s46, 12
	v_add_u32_e32 v125, s6, v124
	global_load_dwordx4 v[92:95], v125, s[8:9] nt
	global_load_dwordx4 v[96:99], v125, s[8:9] offset:1024 nt
	global_load_dwordx4 v[100:103], v125, s[8:9] offset:2048 nt
	global_load_dwordx4 v[104:107], v125, s[8:9] offset:3072 nt
	s_add_i32 s6, s46, s3
	s_min_i32 s6, s6, 0x3fff
	s_lshl_b32 s6, s6, 12
	v_add_u32_e32 v125, s6, v124
	global_load_dwordx4 v[108:111], v125, s[8:9] nt
	global_load_dwordx4 v[112:115], v125, s[8:9] offset:1024 nt
	global_load_dwordx4 v[116:119], v125, s[8:9] offset:2048 nt
	global_load_dwordx4 v[120:123], v125, s[8:9] offset:3072 nt
	s_cmpk_gt_i32 s46, 0x6ff
	s_cbranch_scc1 .LBB0_33
	s_mul_i32 s4, s44, 0x2400
	v_and_b32_e32 v0, 31, v188
	v_readlane_b32 s12, v233, 11
	s_add_i32 s4, s4, 0
	v_lshlrev_b32_e32 v2, 2, v0
	v_mov_b32_e32 v3, 0
	v_readlane_b32 s16, v233, 15
	v_readlane_b32 s17, v233, 16
	v_lshrrev_b32_e32 v4, 5, v218
	v_add_u32_e32 v7, s4, v2
	v_lshl_add_u64 v[0:1], s[16:17], 0, v[2:3]
	v_lshlrev_b32_e32 v2, 3, v188
	v_mul_u32_u24_e32 v8, 0x84, v4
	v_lshrrev_b32_e32 v5, 3, v218
	v_and_b32_e32 v2, 56, v2
	v_mul_u32_u24_e32 v6, 0x84, v2
	v_lshlrev_b32_e32 v2, 1, v2
	v_lshlrev_b32_e32 v9, 2, v5
	v_add_u32_e32 v7, v7, v8
	v_lshl_add_u64 v[2:3], s[54:55], 0, v[2:3]
	v_add3_u32 v6, s4, v6, v9
	s_lshl_b32 s4, s46, 5
	s_lshl_b32 s5, s3, 5
	s_movk_i32 s8, 0x3820
	v_add_u32_e32 v8, 0x400, v7
	v_add_u32_e32 v9, 0x800, v7
	v_add_u32_e32 v10, 0xc00, v7
	v_add_u32_e32 v11, 0x1000, v7
	v_add_u32_e32 v12, 0x1400, v7
	v_add_u32_e32 v13, 0x1800, v7
	v_add_u32_e32 v14, 0x1c00, v7
	s_mov_b32 s9, s46
	v_readlane_b32 s13, v233, 12
	v_readlane_b32 s14, v233, 13
	v_readlane_b32 s15, v233, 14
	v_readlane_b32 s18, v233, 17
	v_readlane_b32 s19, v233, 18
	v_readlane_b32 s20, v233, 19
	v_readlane_b32 s21, v233, 20
	v_readlane_b32 s22, v233, 21
	v_readlane_b32 s23, v233, 22
	v_readlane_b32 s24, v233, 23
	v_readlane_b32 s25, v233, 24
	v_readlane_b32 s26, v233, 25
	v_readlane_b32 s27, v233, 26
.LBB0_32:
	s_mul_hi_i32 s6, s9, 0x92492493
	s_add_i32 s6, s6, s9
	s_lshr_b32 s7, s6, 31
	s_ashr_i32 s6, s6, 6
	s_add_i32 s7, s6, s7
	s_mul_i32 s16, s7, 0xffffff90
	s_lshl_b32 s6, s7, 6
	s_add_i32 s16, s9, s16
	s_cmp_gt_i32 s16, 63
	s_mul_i32 s17, s7, 0xe00
	s_cselect_b32 s16, 8, 0
	s_sub_i32 s16, s16, s17
	s_add_i32 s16, s4, s16
	v_or_b32_e32 v15, s6, v4
	s_ashr_i32 s17, s16, 31
	v_or_b32_e32 v30, 12, v15
	v_or_b32_e32 v32, 14, v15
	v_or_b32_e32 v34, 16, v15
	v_or_b32_e32 v36, 18, v15
	v_or_b32_e32 v38, 20, v15
	v_or_b32_e32 v40, 22, v15
	v_or_b32_e32 v42, 24, v15
	v_or_b32_e32 v44, 26, v15
	v_or_b32_e32 v46, 28, v15
	v_or_b32_e32 v48, 30, v15
	v_or_b32_e32 v50, 32, v15
	v_or_b32_e32 v52, 34, v15
	v_or_b32_e32 v54, 36, v15
	v_lshl_add_u64 v[16:17], s[16:17], 2, v[0:1]
	v_or_b32_e32 v20, 2, v15
	v_or_b32_e32 v22, 4, v15
	v_or_b32_e32 v24, 6, v15
	v_or_b32_e32 v26, 8, v15
	v_or_b32_e32 v28, 10, v15
	v_or_b32_e32 v56, 38, v15
	v_or_b32_e32 v58, 40, v15
	v_or_b32_e32 v60, 42, v15
	v_or_b32_e32 v62, 44, v15
	v_or_b32_e32 v64, 46, v15
	v_or_b32_e32 v66, 48, v15
	v_or_b32_e32 v68, 50, v15
	v_or_b32_e32 v70, 52, v15
	v_or_b32_e32 v72, 54, v15
	v_or_b32_e32 v74, 56, v15
	v_or_b32_e32 v76, 58, v15
	v_or_b32_e32 v78, 60, v15
	v_or_b32_e32 v80, 62, v15
	v_mad_i64_i32 v[18:19], s[16:17], v15, s8, v[16:17]
	v_mad_i64_i32 v[30:31], s[16:17], v30, s8, v[16:17]
	v_mad_i64_i32 v[32:33], s[16:17], v32, s8, v[16:17]
	v_mad_i64_i32 v[34:35], s[16:17], v34, s8, v[16:17]
	v_mad_i64_i32 v[36:37], s[16:17], v36, s8, v[16:17]
	v_mad_i64_i32 v[38:39], s[16:17], v38, s8, v[16:17]
	v_mad_i64_i32 v[40:41], s[16:17], v40, s8, v[16:17]
	v_mad_i64_i32 v[42:43], s[16:17], v42, s8, v[16:17]
	v_mad_i64_i32 v[44:45], s[16:17], v44, s8, v[16:17]
	v_mad_i64_i32 v[46:47], s[16:17], v46, s8, v[16:17]
	v_mad_i64_i32 v[48:49], s[16:17], v48, s8, v[16:17]
	v_mad_i64_i32 v[50:51], s[16:17], v50, s8, v[16:17]
	v_mad_i64_i32 v[52:53], s[16:17], v52, s8, v[16:17]
	v_mad_i64_i32 v[54:55], s[16:17], v54, s8, v[16:17]
	v_mad_i64_i32 v[20:21], s[16:17], v20, s8, v[16:17]
	v_mad_i64_i32 v[22:23], s[16:17], v22, s8, v[16:17]
	v_mad_i64_i32 v[24:25], s[16:17], v24, s8, v[16:17]
	v_mad_i64_i32 v[26:27], s[16:17], v26, s8, v[16:17]
	v_mad_i64_i32 v[28:29], s[16:17], v28, s8, v[16:17]
	v_mad_i64_i32 v[56:57], s[16:17], v56, s8, v[16:17]
	v_mad_i64_i32 v[58:59], s[16:17], v58, s8, v[16:17]
	v_mad_i64_i32 v[60:61], s[16:17], v60, s8, v[16:17]
	v_mad_i64_i32 v[62:63], s[16:17], v62, s8, v[16:17]
	v_mad_i64_i32 v[64:65], s[16:17], v64, s8, v[16:17]
	v_mad_i64_i32 v[66:67], s[16:17], v66, s8, v[16:17]
	v_mad_i64_i32 v[68:69], s[16:17], v68, s8, v[16:17]
	v_mad_i64_i32 v[70:71], s[16:17], v70, s8, v[16:17]
	v_mad_i64_i32 v[72:73], s[16:17], v72, s8, v[16:17]
	v_mad_i64_i32 v[74:75], s[16:17], v74, s8, v[16:17]
	v_mad_i64_i32 v[76:77], s[16:17], v76, s8, v[16:17]
	v_mad_i64_i32 v[78:79], s[16:17], v78, s8, v[16:17]
	v_mad_i64_i32 v[16:17], s[16:17], v80, s8, v[16:17]
	global_load_dword v15, v[18:19], off nt
	global_load_dword v80, v[20:21], off nt
	global_load_dword v81, v[22:23], off nt
	global_load_dword v82, v[24:25], off nt
	global_load_dword v83, v[26:27], off nt
	global_load_dword v84, v[28:29], off nt
	s_nop 0
	global_load_dword v30, v[30:31], off nt
	s_nop 0
	global_load_dword v31, v[32:33], off nt
	s_nop 0
	global_load_dword v32, v[34:35], off nt
	global_load_dword v33, v[36:37], off nt
	s_nop 0
	global_load_dword v34, v[38:39], off nt
	global_load_dword v35, v[40:41], off nt
	global_load_dword v36, v[42:43], off nt
	global_load_dword v37, v[44:45], off nt
	s_nop 0
	global_load_dword v38, v[46:47], off nt
	global_load_dword v39, v[48:49], off nt
	global_load_dword v40, v[50:51], off nt
	global_load_dword v41, v[52:53], off nt
	global_load_dword v42, v[54:55], off nt
	global_load_dword v43, v[56:57], off nt
	global_load_dword v44, v[58:59], off nt
	global_load_dword v45, v[60:61], off nt
	global_load_dword v46, v[62:63], off nt
	global_load_dword v47, v[64:65], off nt
	global_load_dword v48, v[66:67], off nt
	global_load_dword v49, v[68:69], off nt
	global_load_dword v50, v[70:71], off nt
	global_load_dword v51, v[72:73], off nt
	global_load_dword v52, v[74:75], off nt
	global_load_dword v53, v[76:77], off nt
	global_load_dword v54, v[78:79], off nt
	global_load_dword v55, v[16:17], off nt
	s_mul_i32 s16, s7, 0xfffff200
	s_add_i32 s16, s16, s4
	v_add_u32_e32 v22, s16, v5
	v_add_u32_e32 v16, 8, v22
	s_ashr_i32 s7, s6, 31
	v_add_u32_e32 v18, 16, v22
	v_ashrrev_i32_e32 v17, 31, v16
	s_waitcnt vmcnt(30)
	ds_write2_b32 v7, v15, v80 offset1:66
	s_waitcnt vmcnt(28)
	ds_write2_b32 v7, v81, v82 offset0:132 offset1:198
	s_waitcnt vmcnt(26)
	ds_write2_b32 v8, v83, v84 offset0:8 offset1:74
	s_waitcnt vmcnt(24)
	ds_write2_b32 v8, v30, v31 offset0:140 offset1:206
	s_waitcnt vmcnt(22)
	ds_write2_b32 v9, v32, v33 offset0:16 offset1:82
	s_waitcnt vmcnt(20)
	ds_write2_b32 v9, v34, v35 offset0:148 offset1:214
	s_waitcnt vmcnt(18)
	ds_write2_b32 v10, v36, v37 offset0:24 offset1:90
	s_waitcnt vmcnt(16)
	ds_write2_b32 v10, v38, v39 offset0:156 offset1:222
	s_waitcnt vmcnt(14)
	ds_write2_b32 v11, v40, v41 offset0:32 offset1:98
	s_waitcnt vmcnt(12)
	ds_write2_b32 v11, v42, v43 offset0:164 offset1:230
	s_waitcnt vmcnt(10)
	ds_write2_b32 v12, v44, v45 offset0:40 offset1:106
	s_waitcnt vmcnt(8)
	ds_write2_b32 v12, v46, v47 offset0:172 offset1:238
	s_waitcnt vmcnt(6)
	ds_write2_b32 v13, v48, v49 offset0:48 offset1:114
	s_waitcnt vmcnt(4)
	ds_write2_b32 v13, v50, v51 offset0:180 offset1:246
	s_waitcnt vmcnt(2)
	ds_write2_b32 v14, v52, v53 offset0:56 offset1:122
	s_waitcnt vmcnt(0)
	ds_write2_b32 v14, v54, v55 offset0:188 offset1:254
	v_lshl_add_u64 v[20:21], s[6:7], 1, v[2:3]
	v_ashrrev_i32_e32 v19, 31, v18
	v_lshlrev_b64 v[16:17], 11, v[16:17]
	s_waitcnt lgkmcnt(0)
	v_lshlrev_b64 v[18:19], 11, v[18:19]
	v_lshl_add_u64 v[26:27], v[20:21], 0, v[16:17]
	ds_read2_b32 v[16:17], v6 offset1:33
	v_ashrrev_i32_e32 v23, 31, v22
	v_lshl_add_u64 v[28:29], v[20:21], 0, v[18:19]
	s_waitcnt lgkmcnt(0)
	v_cvt_pk_bf16_f32 v16, v16, v17
	ds_read2_b32 v[18:19], v6 offset0:66 offset1:99
	v_lshlrev_b64 v[24:25], 11, v[22:23]
	s_waitcnt lgkmcnt(0)
	v_cvt_pk_bf16_f32 v17, v18, v19
	ds_read2_b32 v[18:19], v6 offset0:132 offset1:165
	v_lshl_add_u64 v[24:25], v[20:21], 0, v[24:25]
	s_waitcnt lgkmcnt(0)
	v_cvt_pk_bf16_f32 v18, v18, v19
	ds_read2_b32 v[30:31], v6 offset0:198 offset1:231
	s_waitcnt lgkmcnt(0)
	v_cvt_pk_bf16_f32 v19, v30, v31
	ds_read2_b32 v[30:31], v6 offset0:8 offset1:41
	global_store_dwordx4 v[24:25], v[16:19], off
	v_add_u32_e32 v22, 24, v22
	v_ashrrev_i32_e32 v23, 31, v22
	s_waitcnt lgkmcnt(0)
	v_cvt_pk_bf16_f32 v16, v30, v31
	ds_read2_b32 v[18:19], v6 offset0:74 offset1:107
	s_waitcnt lgkmcnt(0)
	v_cvt_pk_bf16_f32 v17, v18, v19
	ds_read2_b32 v[18:19], v6 offset0:140 offset1:173
	s_waitcnt lgkmcnt(0)
	v_cvt_pk_bf16_f32 v18, v18, v19
	ds_read2_b32 v[24:25], v6 offset0:206 offset1:239
	s_waitcnt lgkmcnt(0)
	v_cvt_pk_bf16_f32 v19, v24, v25
	ds_read2_b32 v[24:25], v6 offset0:16 offset1:49
	global_store_dwordx4 v[26:27], v[16:19], off
	v_lshlrev_b64 v[22:23], 11, v[22:23]
	v_lshl_add_u64 v[20:21], v[20:21], 0, v[22:23]
	s_waitcnt lgkmcnt(0)
	v_cvt_pk_bf16_f32 v16, v24, v25
	ds_read2_b32 v[18:19], v6 offset0:82 offset1:115
	s_waitcnt lgkmcnt(0)
	v_cvt_pk_bf16_f32 v17, v18, v19
	ds_read2_b32 v[18:19], v6 offset0:148 offset1:181
	s_waitcnt lgkmcnt(0)
	v_cvt_pk_bf16_f32 v18, v18, v19
	ds_read2_b32 v[24:25], v6 offset0:214 offset1:247
	s_waitcnt lgkmcnt(0)
	v_cvt_pk_bf16_f32 v19, v24, v25
	ds_read2_b32 v[24:25], v6 offset0:24 offset1:57
	global_store_dwordx4 v[28:29], v[16:19], off
	s_add_i32 s9, s9, s3
	s_add_i32 s4, s4, s5
	s_waitcnt lgkmcnt(0)
	v_cvt_pk_bf16_f32 v16, v24, v25
	ds_read2_b32 v[18:19], v6 offset0:90 offset1:123
	s_waitcnt lgkmcnt(0)
	v_cvt_pk_bf16_f32 v17, v18, v19
	ds_read2_b32 v[18:19], v6 offset0:156 offset1:189
	s_waitcnt lgkmcnt(0)
	v_cvt_pk_bf16_f32 v18, v18, v19
	ds_read2_b32 v[24:25], v6 offset0:222 offset1:255
	s_waitcnt lgkmcnt(0)
	v_cvt_pk_bf16_f32 v19, v24, v25
	global_store_dwordx4 v[20:21], v[16:19], off
	s_waitcnt lgkmcnt(0)
	s_cmpk_gt_i32 s9, 0x6ff
	s_cbranch_scc0 .LBB0_32

.LBB0_37:
	s_ashr_i32 s47, s46, 31
	ds_read_b128 v[40:43], v57
	ds_read_b128 v[44:47], v57 offset:1024
	ds_read_b128 v[48:51], v57 offset:2048
	ds_read_b128 v[52:55], v57 offset:3072
	ds_read_b128 v[58:61], v57 offset:4096
	ds_read_b128 v[62:65], v57 offset:5120
	s_add_i32 s14, s46, s3
	s_waitcnt vmcnt(12)
	v_mov_b64_e32 v[28:29], v[92:93]
	v_mov_b64_e32 v[30:31], v[94:95]
	v_mov_b64_e32 v[24:25], v[96:97]
	v_mov_b64_e32 v[26:27], v[98:99]
	v_mov_b64_e32 v[20:21], v[100:101]
	v_mov_b64_e32 v[22:23], v[102:103]
	v_mov_b64_e32 v[16:17], v[104:105]
	v_mov_b64_e32 v[18:19], v[106:107]
	v_mov_b64_e32 v[12:13], v[108:109]
	v_mov_b64_e32 v[14:15], v[110:111]
	v_mov_b64_e32 v[8:9], v[112:113]
	v_mov_b64_e32 v[10:11], v[114:115]
	v_mov_b64_e32 v[4:5], v[116:117]
	v_mov_b64_e32 v[6:7], v[118:119]
	v_mov_b64_e32 v[0:1], v[120:121]
	v_mov_b64_e32 v[2:3], v[122:123]
	s_add_i32 s8, s14, s3
	s_min_i32 s8, s8, 0x3fff
	s_ashr_i32 s9, s8, 31
	s_lshl_b64 s[8:9], s[8:9], 12
	v_lshl_add_u64 v[124:125], v[36:37], 0, s[8:9]
	global_load_dwordx4 v[92:95], v[124:125], off nt
	global_load_dwordx4 v[96:99], v[124:125], off offset:1024 nt
	global_load_dwordx4 v[100:103], v[124:125], off offset:2048 nt
	global_load_dwordx4 v[104:107], v[124:125], off offset:3072 nt
	s_add_i32 s8, s14, s3
	s_add_i32 s8, s8, s3
	s_min_i32 s8, s8, 0x3fff
	s_ashr_i32 s9, s8, 31
	s_lshl_b64 s[8:9], s[8:9], 12
	v_lshl_add_u64 v[124:125], v[36:37], 0, s[8:9]
	global_load_dwordx4 v[108:111], v[124:125], off nt
	global_load_dwordx4 v[112:115], v[124:125], off offset:1024 nt
	global_load_dwordx4 v[116:119], v[124:125], off offset:2048 nt
	global_load_dwordx4 v[120:123], v[124:125], off offset:3072 nt
	v_mul_f32_e32 v32, v29, v29
	v_mul_f32_e32 v66, v31, v31
	v_mul_f32_e32 v67, v25, v25
	v_mul_f32_e32 v68, v27, v27
	v_mul_f32_e32 v69, v21, v21
	v_mul_f32_e32 v70, v23, v23
	s_waitcnt lgkmcnt(5)
	v_mul_f32_e32 v41, v29, v41
	v_fmac_f32_e32 v32, v28, v28
	v_fmac_f32_e32 v66, v30, v30
	v_fmac_f32_e32 v67, v24, v24
	v_fmac_f32_e32 v68, v26, v26
	v_mul_f32_e32 v71, v17, v17
	v_mul_f32_e32 v72, v19, v19
	v_mul_f32_e32 v43, v31, v43
	v_fmac_f32_e32 v69, v20, v20
	v_fmac_f32_e32 v70, v22, v22
	v_fmac_f32_e32 v41, v28, v40
	v_add_f32_e32 v32, v32, v66
	v_add_f32_e32 v40, v67, v68
	s_waitcnt lgkmcnt(4)
	v_mul_f32_e32 v45, v25, v45
	v_fmac_f32_e32 v71, v16, v16
	v_fmac_f32_e32 v72, v18, v18
	v_fmac_f32_e32 v43, v30, v42
	v_add_f32_e32 v42, v69, v70
	v_add_f32_e32 v32, v32, v40
	v_fmac_f32_e32 v45, v24, v44
	v_add_f32_e32 v44, v71, v72
	v_add_f32_e32 v32, v32, v42
	v_add_f32_e32 v32, v32, v44
	v_mul_f32_e32 v47, v27, v47
	s_waitcnt lgkmcnt(3)
	v_mul_f32_e32 v49, v21, v49
	v_add_f32_dpp v32, v32, v32 quad_perm:[1,0,3,2] row_mask:0xf bank_mask:0xf bound_ctrl:1
	v_mul_f32_e32 v51, v23, v51
	v_fmac_f32_e32 v47, v26, v46
	v_add_f32_dpp v32, v32, v32 quad_perm:[2,3,0,1] row_mask:0xf bank_mask:0xf bound_ctrl:1
	v_add_f32_e32 v41, v41, v43
	s_waitcnt lgkmcnt(2)
	v_mul_f32_e32 v53, v17, v53
	v_add_f32_dpp v32, v32, v32 row_half_mirror row_mask:0xf bank_mask:0xf bound_ctrl:1
	v_mul_f32_e32 v55, v19, v55
	v_fmac_f32_e32 v49, v20, v48
	v_add_f32_dpp v32, v32, v32 row_mirror row_mask:0xf bank_mask:0xf bound_ctrl:1
	v_mov_b32_e32 v42, v32
	s_nop 1
	v_permlane16_swap_b32_e32 v32, v42
	v_add_f32_e32 v32, v32, v42
	v_fmac_f32_e32 v51, v22, v50
	v_add_f32_e32 v43, v45, v47
	v_add_f32_e32 v40, 0, v41
	v_mov_b32_e32 v42, v32
	v_fmac_f32_e32 v53, v16, v52
	v_fmac_f32_e32 v55, v18, v54
	v_add_f32_e32 v45, v49, v51
	v_add_f32_e32 v40, v40, v43
	v_permlane32_swap_b32_e32 v32, v42
	v_add_f32_e32 v46, v53, v55
	v_add_f32_e32 v40, v40, v45
	v_add_f32_e32 v32, v32, v42
	v_add_f32_e32 v40, v40, v46
	v_fmamk_f32 v32, v32, 0x3a800000, v56
	s_waitcnt lgkmcnt(1)
	v_mul_f32_e32 v59, v29, v59
	v_mul_f32_e32 v61, v31, v61
	v_add_f32_dpp v40, v40, v40 quad_perm:[1,0,3,2] row_mask:0xf bank_mask:0xf bound_ctrl:1
	v_mul_f32_e32 v42, 0x4b800000, v32
	v_cmp_gt_f32_e64 s[8:9], s52, v32
	v_fmac_f32_e32 v59, v28, v58
	v_fmac_f32_e32 v61, v30, v60
	v_add_f32_dpp v40, v40, v40 quad_perm:[2,3,0,1] row_mask:0xf bank_mask:0xf bound_ctrl:1
	v_cndmask_b32_e64 v32, v32, v42, s[8:9]
	v_add_f32_e32 v47, v59, v61
	v_add_f32_dpp v40, v40, v40 row_half_mirror row_mask:0xf bank_mask:0xf bound_ctrl:1
	v_rsq_f32_e32 v32, v32
	v_add_f32_e32 v41, 0, v47
	v_add_f32_dpp v40, v40, v40 row_mirror row_mask:0xf bank_mask:0xf bound_ctrl:1
	ds_read_b128 v[44:47], v57 offset:6144
	ds_read_b128 v[48:51], v57 offset:7168
	v_mov_b32_e32 v43, v40
	s_waitcnt lgkmcnt(2)
	v_mul_f32_e32 v63, v25, v63
	v_mul_f32_e32 v65, v27, v65
	v_permlane16_swap_b32_e32 v40, v43
	v_fmac_f32_e32 v63, v24, v62
	v_add_f32_e32 v40, v40, v43
	v_mul_f32_e32 v43, 0x45800000, v32
	v_fmac_f32_e32 v65, v26, v64
	v_cndmask_b32_e64 v32, v32, v43, s[8:9]
	v_add_f32_e32 v43, v63, v65
	v_add_f32_e32 v41, v41, v43
	s_waitcnt lgkmcnt(1)
	v_mul_f32_e32 v43, v21, v45
	v_fmac_f32_e32 v43, v20, v44
	v_mul_f32_e32 v44, v23, v47
	v_fmac_f32_e32 v44, v22, v46
	v_add_f32_e32 v43, v43, v44
	v_add_f32_e32 v41, v41, v43
	s_waitcnt lgkmcnt(0)
	v_mul_f32_e32 v43, v17, v49
	v_mul_f32_e32 v44, v19, v51
	v_fmac_f32_e32 v43, v16, v48
	v_fmac_f32_e32 v44, v18, v50
	v_add_f32_e32 v43, v43, v44
	ds_read_b128 v[44:47], v57 offset:8192
	ds_read_b128 v[48:51], v57 offset:9216
	v_add_f32_e32 v41, v41, v43
	v_mov_b32_e32 v42, v40
	s_nop 1
	v_permlane32_swap_b32_e32 v40, v42
	s_waitcnt lgkmcnt(1)
	v_mul_f32_e32 v45, v29, v45
	v_fmac_f32_e32 v45, v28, v44
	v_mul_f32_e32 v44, v31, v47
	v_fmac_f32_e32 v44, v30, v46
	v_add_f32_e32 v44, v45, v44
	s_waitcnt lgkmcnt(0)
	v_mul_f32_e32 v49, v25, v49
	v_add_f32_e32 v52, 0, v44
	v_fmac_f32_e32 v49, v24, v48
	v_mul_f32_e32 v48, v27, v51
	ds_read_b128 v[44:47], v57 offset:10240
	v_fmac_f32_e32 v48, v26, v50
	v_add_f32_e32 v48, v49, v48
	v_add_f32_e32 v52, v52, v48
	ds_read_b128 v[48:51], v57 offset:11264
	s_waitcnt lgkmcnt(1)
	v_mul_f32_e32 v45, v21, v45
	v_fmac_f32_e32 v45, v20, v44
	v_mul_f32_e32 v44, v23, v47
	v_fmac_f32_e32 v44, v22, v46
	v_add_f32_e32 v44, v45, v44
	s_waitcnt lgkmcnt(0)
	v_mul_f32_e32 v45, v17, v49
	v_mul_f32_e32 v46, v19, v51
	v_fmac_f32_e32 v45, v16, v48
	v_fmac_f32_e32 v46, v18, v50
	v_add_f32_e32 v44, v52, v44
	v_add_f32_e32 v45, v45, v46
	v_add_f32_e32 v44, v44, v45
	ds_read_b128 v[48:51], v57 offset:12288
	ds_read_b128 v[52:55], v57 offset:13312
	v_add_f32_dpp v44, v44, v44 quad_perm:[1,0,3,2] row_mask:0xf bank_mask:0xf bound_ctrl:1
	v_add_f32_dpp v41, v41, v41 quad_perm:[1,0,3,2] row_mask:0xf bank_mask:0xf bound_ctrl:1
	s_waitcnt lgkmcnt(1)
	v_mul_f32_e32 v47, v31, v51
	v_add_f32_dpp v44, v44, v44 quad_perm:[2,3,0,1] row_mask:0xf bank_mask:0xf bound_ctrl:1
	v_fmac_f32_e32 v47, v30, v50
	v_add_f32_dpp v41, v41, v41 quad_perm:[2,3,0,1] row_mask:0xf bank_mask:0xf bound_ctrl:1
	v_add_f32_dpp v44, v44, v44 row_half_mirror row_mask:0xf bank_mask:0xf bound_ctrl:1
	s_nop 0
	v_add_f32_dpp v41, v41, v41 row_half_mirror row_mask:0xf bank_mask:0xf bound_ctrl:1
	v_add_f32_dpp v44, v44, v44 row_mirror row_mask:0xf bank_mask:0xf bound_ctrl:1
	v_mov_b32_e32 v45, v44
	s_nop 1
	v_permlane16_swap_b32_e32 v44, v45
	v_add_f32_e32 v44, v44, v45
	v_mul_f32_e32 v45, v29, v49
	v_fmac_f32_e32 v45, v28, v48
	ds_read_b128 v[48:51], v57 offset:14336
	v_add_f32_e32 v45, v45, v47
	s_waitcnt lgkmcnt(1)
	v_mul_f32_e32 v47, v25, v53
	v_fmac_f32_e32 v47, v24, v52
	v_mul_f32_e32 v52, v27, v55
	v_fmac_f32_e32 v52, v26, v54
	v_add_f32_e32 v45, 0, v45
	v_add_f32_e32 v47, v47, v52
	ds_read_b128 v[52:55], v57 offset:15360
	v_add_f32_e32 v45, v45, v47
	s_waitcnt lgkmcnt(1)
	v_mul_f32_e32 v47, v21, v49
	v_fmac_f32_e32 v47, v20, v48
	v_mul_f32_e32 v48, v23, v51
	v_fmac_f32_e32 v48, v22, v50
	v_add_f32_e32 v47, v47, v48
	v_add_f32_e32 v45, v45, v47
	s_waitcnt lgkmcnt(0)
	v_mul_f32_e32 v47, v17, v53
	v_mul_f32_e32 v48, v19, v55
	v_fmac_f32_e32 v47, v16, v52
	v_fmac_f32_e32 v48, v18, v54
	v_add_f32_e32 v47, v47, v48
	ds_read_b128 v[48:51], v57 offset:16384
	ds_read_b128 v[52:55], v57 offset:17408
	v_add_f32_e32 v45, v45, v47
	v_add_f32_dpp v41, v41, v41 row_mirror row_mask:0xf bank_mask:0xf bound_ctrl:1
	v_mov_b32_e32 v43, v41
	s_waitcnt lgkmcnt(1)
	v_mul_f32_e32 v49, v29, v49
	v_fmac_f32_e32 v49, v28, v48
	v_mul_f32_e32 v48, v31, v51
	v_fmac_f32_e32 v48, v30, v50
	v_add_f32_e32 v48, v49, v48
	s_waitcnt lgkmcnt(0)
	v_mul_f32_e32 v53, v25, v53
	v_add_f32_e32 v58, 0, v48
	v_fmac_f32_e32 v53, v24, v52
	v_mul_f32_e32 v52, v27, v55
	ds_read_b128 v[48:51], v57 offset:18432
	v_fmac_f32_e32 v52, v26, v54
	v_add_f32_e32 v52, v53, v52
	v_add_f32_e32 v58, v58, v52
	ds_read_b128 v[52:55], v57 offset:19456
	s_waitcnt lgkmcnt(1)
	v_mul_f32_e32 v49, v21, v49
	v_fmac_f32_e32 v49, v20, v48
	v_mul_f32_e32 v48, v23, v51
	v_fmac_f32_e32 v48, v22, v50
	v_add_f32_e32 v48, v49, v48
	s_waitcnt lgkmcnt(0)
	v_mul_f32_e32 v49, v17, v53
	v_mul_f32_e32 v50, v19, v55
	v_fmac_f32_e32 v49, v16, v52
	v_fmac_f32_e32 v50, v18, v54
	v_add_f32_e32 v48, v58, v48
	v_add_f32_e32 v49, v49, v50
	v_add_f32_e32 v48, v48, v49
	ds_read_b128 v[52:55], v57 offset:20480
	ds_read_b128 v[58:61], v57 offset:21504
	v_add_f32_dpp v48, v48, v48 quad_perm:[1,0,3,2] row_mask:0xf bank_mask:0xf bound_ctrl:1
	v_add_f32_dpp v45, v45, v45 quad_perm:[1,0,3,2] row_mask:0xf bank_mask:0xf bound_ctrl:1
	v_permlane16_swap_b32_e32 v41, v43
	v_add_f32_dpp v48, v48, v48 quad_perm:[2,3,0,1] row_mask:0xf bank_mask:0xf bound_ctrl:1
	s_waitcnt lgkmcnt(1)
	v_mul_f32_e32 v51, v31, v55
	v_fmac_f32_e32 v51, v30, v54
	v_add_f32_dpp v48, v48, v48 row_half_mirror row_mask:0xf bank_mask:0xf bound_ctrl:1
	v_add_f32_dpp v45, v45, v45 quad_perm:[2,3,0,1] row_mask:0xf bank_mask:0xf bound_ctrl:1
	v_add_f32_e32 v41, v41, v43
	v_add_f32_dpp v48, v48, v48 row_mirror row_mask:0xf bank_mask:0xf bound_ctrl:1
	v_mov_b32_e32 v49, v48
	s_nop 1
	v_permlane16_swap_b32_e32 v48, v49
	v_add_f32_e32 v48, v48, v49
	v_mul_f32_e32 v49, v29, v53
	v_fmac_f32_e32 v49, v28, v52
	ds_read_b128 v[52:55], v57 offset:22528
	v_add_f32_e32 v49, v49, v51
	s_waitcnt lgkmcnt(1)
	v_mul_f32_e32 v51, v25, v59
	v_fmac_f32_e32 v51, v24, v58
	v_mul_f32_e32 v58, v27, v61
	v_fmac_f32_e32 v58, v26, v60
	v_add_f32_e32 v49, 0, v49
	v_add_f32_e32 v51, v51, v58
	ds_read_b128 v[58:61], v57 offset:23552
	v_add_f32_e32 v49, v49, v51
	s_waitcnt lgkmcnt(1)
	v_mul_f32_e32 v51, v21, v53
	v_fmac_f32_e32 v51, v20, v52
	v_mul_f32_e32 v52, v23, v55
	v_fmac_f32_e32 v52, v22, v54
	v_add_f32_e32 v51, v51, v52
	v_add_f32_e32 v49, v49, v51
	s_waitcnt lgkmcnt(0)
	v_mul_f32_e32 v51, v17, v59
	v_mul_f32_e32 v52, v19, v61
	v_fmac_f32_e32 v51, v16, v58
	v_fmac_f32_e32 v52, v18, v60
	v_add_f32_e32 v51, v51, v52
	ds_read_b128 v[52:55], v57 offset:24576
	ds_read_b128 v[58:61], v57 offset:25600
	v_add_f32_e32 v49, v49, v51
	v_add_f32_dpp v45, v45, v45 row_half_mirror row_mask:0xf bank_mask:0xf bound_ctrl:1
	v_mov_b32_e32 v43, v41
	s_waitcnt lgkmcnt(1)
	v_mul_f32_e32 v53, v29, v53
	v_fmac_f32_e32 v53, v28, v52
	v_mul_f32_e32 v52, v31, v55
	v_fmac_f32_e32 v52, v30, v54
	v_add_f32_e32 v52, v53, v52
	s_waitcnt lgkmcnt(0)
	v_mul_f32_e32 v59, v25, v59
	v_add_f32_e32 v62, 0, v52
	v_fmac_f32_e32 v59, v24, v58
	v_mul_f32_e32 v58, v27, v61
	ds_read_b128 v[52:55], v57 offset:26624
	v_fmac_f32_e32 v58, v26, v60
	v_add_f32_e32 v58, v59, v58
	v_add_f32_e32 v62, v62, v58
	ds_read_b128 v[58:61], v57 offset:27648
	s_waitcnt lgkmcnt(1)
	v_mul_f32_e32 v53, v21, v53
	v_fmac_f32_e32 v53, v20, v52
	v_mul_f32_e32 v52, v23, v55
	v_fmac_f32_e32 v52, v22, v54
	v_add_f32_e32 v52, v53, v52
	s_waitcnt lgkmcnt(0)
	v_mul_f32_e32 v53, v17, v59
	v_mul_f32_e32 v54, v19, v61
	v_fmac_f32_e32 v53, v16, v58
	v_fmac_f32_e32 v54, v18, v60
	v_add_f32_e32 v52, v62, v52
	v_add_f32_e32 v53, v53, v54
	v_add_f32_e32 v52, v52, v53
	ds_read_b128 v[58:61], v57 offset:28672
	ds_read_b128 v[62:65], v57 offset:29696
	v_add_f32_dpp v52, v52, v52 quad_perm:[1,0,3,2] row_mask:0xf bank_mask:0xf bound_ctrl:1
	v_add_f32_dpp v49, v49, v49 quad_perm:[1,0,3,2] row_mask:0xf bank_mask:0xf bound_ctrl:1
	v_add_f32_dpp v45, v45, v45 row_mirror row_mask:0xf bank_mask:0xf bound_ctrl:1
	v_add_f32_dpp v52, v52, v52 quad_perm:[2,3,0,1] row_mask:0xf bank_mask:0xf bound_ctrl:1
	s_waitcnt lgkmcnt(1)
	v_mul_f32_e32 v55, v31, v61
	v_fmac_f32_e32 v55, v30, v60
	v_add_f32_dpp v52, v52, v52 row_half_mirror row_mask:0xf bank_mask:0xf bound_ctrl:1
	v_add_f32_dpp v49, v49, v49 quad_perm:[2,3,0,1] row_mask:0xf bank_mask:0xf bound_ctrl:1
	v_mov_b32_e32 v47, v45
	v_add_f32_dpp v52, v52, v52 row_mirror row_mask:0xf bank_mask:0xf bound_ctrl:1
	v_mov_b32_e32 v53, v52
	s_nop 1
	v_permlane16_swap_b32_e32 v52, v53
	v_add_f32_e32 v52, v52, v53
	v_mul_f32_e32 v53, v29, v59
	v_fmac_f32_e32 v53, v28, v58
	ds_read_b128 v[58:61], v57 offset:30720
	v_add_f32_e32 v53, v53, v55
	s_waitcnt lgkmcnt(1)
	v_mul_f32_e32 v55, v25, v63
	v_fmac_f32_e32 v55, v24, v62
	v_mul_f32_e32 v62, v27, v65
	v_fmac_f32_e32 v62, v26, v64
	v_add_f32_e32 v53, 0, v53
	v_add_f32_e32 v55, v55, v62
	ds_read_b128 v[62:65], v57 offset:31744
	v_add_f32_e32 v53, v53, v55
	s_waitcnt lgkmcnt(1)
	v_mul_f32_e32 v55, v21, v59
	v_fmac_f32_e32 v55, v20, v58
	v_mul_f32_e32 v58, v23, v61
	v_fmac_f32_e32 v58, v22, v60
	v_add_f32_e32 v55, v55, v58
	v_add_f32_e32 v53, v53, v55
	s_waitcnt lgkmcnt(0)
	v_mul_f32_e32 v55, v17, v63
	v_mul_f32_e32 v58, v19, v65
	v_fmac_f32_e32 v55, v16, v62
	v_fmac_f32_e32 v58, v18, v64
	v_add_f32_e32 v55, v55, v58
	v_add_f32_e32 v53, v53, v55
	v_add_f32_dpp v49, v49, v49 row_half_mirror row_mask:0xf bank_mask:0xf bound_ctrl:1
	v_permlane16_swap_b32_e32 v45, v47
	v_add_f32_dpp v53, v53, v53 quad_perm:[1,0,3,2] row_mask:0xf bank_mask:0xf bound_ctrl:1
	v_add_f32_dpp v49, v49, v49 row_mirror row_mask:0xf bank_mask:0xf bound_ctrl:1
	v_mov_b32_e32 v51, v49
	v_add_f32_dpp v53, v53, v53 quad_perm:[2,3,0,1] row_mask:0xf bank_mask:0xf bound_ctrl:1
	s_nop 0
	v_permlane16_swap_b32_e32 v49, v51
	v_add_f32_dpp v53, v53, v53 row_half_mirror row_mask:0xf bank_mask:0xf bound_ctrl:1
	v_add_f32_e32 v45, v45, v47
	v_add_f32_e32 v49, v49, v51
	v_add_f32_dpp v53, v53, v53 row_mirror row_mask:0xf bank_mask:0xf bound_ctrl:1
	v_mov_b32_e32 v55, v53
	s_nop 1
	v_permlane16_swap_b32_e32 v53, v55
	v_add_f32_e32 v53, v53, v55
	v_mov_b32_e32 v46, v44
	v_mov_b32_e32 v47, v45
	v_mov_b32_e32 v50, v48
	v_mov_b32_e32 v51, v49
	v_mov_b32_e32 v54, v52
	v_mov_b32_e32 v55, v53
	v_permlane32_swap_b32_e32 v41, v43
	v_permlane32_swap_b32_e32 v44, v46
	v_permlane32_swap_b32_e32 v45, v47
	v_permlane32_swap_b32_e32 v48, v50
	v_permlane32_swap_b32_e32 v49, v51
	v_permlane32_swap_b32_e32 v52, v54
	v_permlane32_swap_b32_e32 v53, v55
	s_and_saveexec_b64 s[8:9], vcc
	s_cbranch_execz .LBB0_39
	s_lshl_b64 s[16:17], s[46:47], 5
	v_pk_add_f32 v[40:41], v[40:41], v[42:43]
	v_pk_add_f32 v[42:43], v[44:45], v[46:47]
	s_add_u32 s16, s4, s16
	v_pk_mul_f32 v[42:43], v[32:33], v[42:43] op_sel_hi:[0,1]
	v_pk_mul_f32 v[40:41], v[32:33], v[40:41] op_sel_hi:[0,1]
	v_pk_add_f32 v[44:45], v[48:49], v[50:51]
	v_pk_add_f32 v[46:47], v[52:53], v[54:55]
	s_addc_u32 s17, s5, s17
	v_pk_mul_f32 v[46:47], v[32:33], v[46:47] op_sel_hi:[0,1]
	v_pk_mul_f32 v[44:45], v[32:33], v[44:45] op_sel_hi:[0,1]
	global_store_dwordx4 v33, v[40:43], s[16:17]
	global_store_dwordx4 v33, v[44:47], s[16:17] offset:16

.LBB0_119:
	s_cmpk_gt_i32 s4, 0x1ff
	s_mov_b64 s[56:57], -1
	s_cbranch_scc0 .LBB0_127
	s_cmpk_gt_u32 s4, 0xcff
	s_cbranch_scc0 .LBB0_122
	s_and_b32 s50, s62, 0x7fffffc0
	s_add_i32 s56, s50, 0xffffe600
	s_and_b32 s58, s60, 0x3e0
	v_or_b32_e32 v0, s56, v46
	s_lshl_b32 s54, s58, 2
	v_or_b32_e32 v18, 2, v0
	v_mov_b32_e32 v19, v1
	v_or_b32_e32 v20, 4, v0
	v_mov_b32_e32 v21, v1
	v_or_b32_e32 v22, 6, v0
	v_mov_b32_e32 v23, v1
	v_or_b32_e32 v24, 8, v0
	v_mov_b32_e32 v25, v1
	v_or_b32_e32 v26, 10, v0
	v_mov_b32_e32 v27, v1
	v_or_b32_e32 v28, 12, v0
	v_mov_b32_e32 v29, v1
	v_lshl_add_u64 v[14:15], v[2:3], 0, s[54:55]
	v_lshlrev_b64 v[16:17], 12, v[0:1]
	v_lshlrev_b64 v[18:19], 12, v[18:19]
	v_lshlrev_b64 v[20:21], 12, v[20:21]
	v_lshlrev_b64 v[22:23], 12, v[22:23]
	v_lshlrev_b64 v[24:25], 12, v[24:25]
	v_lshlrev_b64 v[26:27], 12, v[26:27]
	v_lshlrev_b64 v[28:29], 12, v[28:29]
	v_or_b32_e32 v30, 14, v0
	v_mov_b32_e32 v31, v1
	v_lshl_add_u64 v[16:17], v[14:15], 0, v[16:17]
	v_lshl_add_u64 v[18:19], v[14:15], 0, v[18:19]
	v_lshl_add_u64 v[20:21], v[14:15], 0, v[20:21]
	v_lshl_add_u64 v[22:23], v[14:15], 0, v[22:23]
	v_lshl_add_u64 v[24:25], v[14:15], 0, v[24:25]
	v_lshl_add_u64 v[26:27], v[14:15], 0, v[26:27]
	v_lshl_add_u64 v[28:29], v[14:15], 0, v[28:29]
	v_lshlrev_b64 v[30:31], 12, v[30:31]
	v_lshl_add_u64 v[30:31], v[14:15], 0, v[30:31]
	global_load_dword v32, v[16:17], off nt
	global_load_dword v33, v[18:19], off nt
	global_load_dword v34, v[20:21], off nt
	global_load_dword v35, v[22:23], off nt
	global_load_dword v36, v[24:25], off nt
	global_load_dword v37, v[26:27], off nt
	global_load_dword v38, v[28:29], off nt
	global_load_dword v39, v[30:31], off nt
	v_or_b32_e32 v16, 16, v0
	v_mov_b32_e32 v17, v1
	v_or_b32_e32 v18, 18, v0
	v_mov_b32_e32 v19, v1
	v_or_b32_e32 v20, 20, v0
	v_mov_b32_e32 v21, v1
	v_or_b32_e32 v22, 22, v0
	v_mov_b32_e32 v23, v1
	v_or_b32_e32 v24, 24, v0
	v_mov_b32_e32 v25, v1
	v_or_b32_e32 v26, 26, v0
	v_mov_b32_e32 v27, v1
	v_or_b32_e32 v28, 28, v0
	v_mov_b32_e32 v29, v1
	v_lshlrev_b64 v[16:17], 12, v[16:17]
	v_lshlrev_b64 v[18:19], 12, v[18:19]
	v_lshlrev_b64 v[20:21], 12, v[20:21]
	v_lshlrev_b64 v[22:23], 12, v[22:23]
	v_lshlrev_b64 v[24:25], 12, v[24:25]
	v_lshlrev_b64 v[26:27], 12, v[26:27]
	v_lshlrev_b64 v[28:29], 12, v[28:29]
	v_or_b32_e32 v30, 30, v0
	v_mov_b32_e32 v31, v1
	v_lshl_add_u64 v[16:17], v[14:15], 0, v[16:17]
	v_lshl_add_u64 v[18:19], v[14:15], 0, v[18:19]
	v_lshl_add_u64 v[20:21], v[14:15], 0, v[20:21]
	v_lshl_add_u64 v[22:23], v[14:15], 0, v[22:23]
	v_lshl_add_u64 v[24:25], v[14:15], 0, v[24:25]
	v_lshl_add_u64 v[26:27], v[14:15], 0, v[26:27]
	v_lshl_add_u64 v[28:29], v[14:15], 0, v[28:29]
	v_lshlrev_b64 v[30:31], 12, v[30:31]
	v_lshl_add_u64 v[30:31], v[14:15], 0, v[30:31]
	global_load_dword v40, v[16:17], off nt
	global_load_dword v41, v[18:19], off nt
	global_load_dword v42, v[20:21], off nt
	global_load_dword v43, v[22:23], off nt
	global_load_dword v44, v[24:25], off nt
	global_load_dword v45, v[26:27], off nt
	global_load_dword v60, v[28:29], off nt
	global_load_dword v61, v[30:31], off nt
	v_or_b32_e32 v16, 32, v0
	v_mov_b32_e32 v17, v1
	v_or_b32_e32 v18, 34, v0
	v_mov_b32_e32 v19, v1
	v_or_b32_e32 v20, 36, v0
	v_mov_b32_e32 v21, v1
	v_or_b32_e32 v22, 38, v0
	v_mov_b32_e32 v23, v1
	v_or_b32_e32 v24, 40, v0
	v_mov_b32_e32 v25, v1
	v_or_b32_e32 v26, 42, v0
	v_mov_b32_e32 v27, v1
	v_or_b32_e32 v28, 44, v0
	v_mov_b32_e32 v29, v1
	v_lshlrev_b64 v[16:17], 12, v[16:17]
	v_lshlrev_b64 v[18:19], 12, v[18:19]
	v_lshlrev_b64 v[20:21], 12, v[20:21]
	v_lshlrev_b64 v[22:23], 12, v[22:23]
	v_lshlrev_b64 v[24:25], 12, v[24:25]
	v_lshlrev_b64 v[26:27], 12, v[26:27]
	v_lshlrev_b64 v[28:29], 12, v[28:29]
	v_or_b32_e32 v30, 46, v0
	v_mov_b32_e32 v31, v1
	v_lshl_add_u64 v[16:17], v[14:15], 0, v[16:17]
	v_lshl_add_u64 v[18:19], v[14:15], 0, v[18:19]
	v_lshl_add_u64 v[20:21], v[14:15], 0, v[20:21]
	v_lshl_add_u64 v[22:23], v[14:15], 0, v[22:23]
	v_lshl_add_u64 v[24:25], v[14:15], 0, v[24:25]
	v_lshl_add_u64 v[26:27], v[14:15], 0, v[26:27]
	v_lshl_add_u64 v[28:29], v[14:15], 0, v[28:29]
	v_lshlrev_b64 v[30:31], 12, v[30:31]
	v_lshl_add_u64 v[30:31], v[14:15], 0, v[30:31]
	global_load_dword v62, v[16:17], off nt
	global_load_dword v63, v[18:19], off nt
	global_load_dword v64, v[20:21], off nt
	global_load_dword v65, v[22:23], off nt
	global_load_dword v66, v[24:25], off nt
	global_load_dword v67, v[26:27], off nt
	global_load_dword v68, v[28:29], off nt
	global_load_dword v69, v[30:31], off nt
	v_or_b32_e32 v16, 48, v0
	v_mov_b32_e32 v17, v1
	v_or_b32_e32 v18, 50, v0
	v_mov_b32_e32 v19, v1
	v_or_b32_e32 v20, 52, v0
	v_mov_b32_e32 v21, v1
	v_or_b32_e32 v22, 54, v0
	v_mov_b32_e32 v23, v1
	v_or_b32_e32 v24, 56, v0
	v_mov_b32_e32 v25, v1
	v_or_b32_e32 v26, 58, v0
	v_mov_b32_e32 v27, v1
	v_or_b32_e32 v28, 60, v0
	v_mov_b32_e32 v29, v1
	v_or_b32_e32 v0, 62, v0
	v_lshlrev_b64 v[16:17], 12, v[16:17]
	v_lshlrev_b64 v[18:19], 12, v[18:19]
	v_lshlrev_b64 v[20:21], 12, v[20:21]
	v_lshlrev_b64 v[22:23], 12, v[22:23]
	v_lshlrev_b64 v[24:25], 12, v[24:25]
	v_lshlrev_b64 v[26:27], 12, v[26:27]
	v_lshlrev_b64 v[28:29], 12, v[28:29]
	v_lshlrev_b64 v[30:31], 12, v[0:1]
	v_lshl_add_u64 v[16:17], v[14:15], 0, v[16:17]
	v_lshl_add_u64 v[18:19], v[14:15], 0, v[18:19]
	v_lshl_add_u64 v[20:21], v[14:15], 0, v[20:21]
	v_lshl_add_u64 v[22:23], v[14:15], 0, v[22:23]
	v_lshl_add_u64 v[24:25], v[14:15], 0, v[24:25]
	v_lshl_add_u64 v[26:27], v[14:15], 0, v[26:27]
	v_lshl_add_u64 v[28:29], v[14:15], 0, v[28:29]
	v_lshl_add_u64 v[14:15], v[14:15], 0, v[30:31]
	global_load_dword v0, v[16:17], off nt
	s_nop 0
	global_load_dword v16, v[18:19], off nt
	global_load_dword v17, v[20:21], off nt
	s_nop 0
	global_load_dword v18, v[22:23], off nt
	global_load_dword v19, v[24:25], off nt
	global_load_dword v20, v[26:27], off nt
	global_load_dword v21, v[28:29], off nt
	s_nop 0
	global_load_dword v14, v[14:15], off nt
	s_waitcnt vmcnt(0)
	ds_write2_b32 v47, v32, v33 offset1:66
	ds_write2_b32 v47, v34, v35 offset0:132 offset1:198
	ds_write2_b32 v53, v36, v37 offset0:8 offset1:74
	ds_write2_b32 v53, v38, v39 offset0:140 offset1:206
	ds_write2_b32 v54, v40, v41 offset0:16 offset1:82
	ds_write2_b32 v54, v42, v43 offset0:148 offset1:214
	ds_write2_b32 v55, v44, v45 offset0:24 offset1:90
	ds_write2_b32 v55, v60, v61 offset0:156 offset1:222
	ds_write2_b32 v56, v62, v63 offset0:32 offset1:98
	ds_write2_b32 v56, v64, v65 offset0:164 offset1:230
	ds_write2_b32 v57, v66, v67 offset0:40 offset1:106
	ds_write2_b32 v57, v68, v69 offset0:172 offset1:238
	ds_write2_b32 v58, v0, v16 offset0:48 offset1:114
	ds_write2_b32 v58, v17, v18 offset0:180 offset1:246
	ds_write2_b32 v59, v19, v20 offset0:56 offset1:122
	ds_write2_b32 v59, v21, v14 offset0:188 offset1:254
	s_waitcnt lgkmcnt(0)
	ds_read2_b32 v[14:15], v49 offset1:33
	v_or_b32_e32 v0, s58, v48
	s_waitcnt lgkmcnt(0)
	v_cvt_pk_bf16_f32 v14, v14, v15
	ds_read2_b32 v[16:17], v49 offset0:66 offset1:99
	s_mov_b32 s57, s55
	v_mul_u32_u24_e32 v0, 0xb00, v0
	s_waitcnt lgkmcnt(0)
	v_cvt_pk_bf16_f32 v15, v16, v17
	ds_read2_b32 v[16:17], v49 offset0:132 offset1:165
	v_lshl_add_u64 v[20:21], s[56:57], 1, v[4:5]
	v_lshlrev_b32_e32 v0, 1, v0
	s_waitcnt lgkmcnt(0)
	v_cvt_pk_bf16_f32 v16, v16, v17
	ds_read2_b32 v[18:19], v49 offset0:198 offset1:231
	s_waitcnt lgkmcnt(0)
	v_cvt_pk_bf16_f32 v17, v18, v19
	v_lshl_add_u64 v[22:23], v[20:21], 0, v[0:1]
	v_or_b32_e32 v0, s58, v50
	ds_read2_b32 v[18:19], v49 offset0:8 offset1:41
	global_store_dwordx4 v[22:23], v[14:17], off
	v_mul_u32_u24_e32 v0, 0xb00, v0
	v_lshlrev_b32_e32 v0, 1, v0
	s_waitcnt lgkmcnt(0)
	v_cvt_pk_bf16_f32 v14, v18, v19
	ds_read2_b32 v[16:17], v49 offset0:74 offset1:107
	s_waitcnt lgkmcnt(0)
	v_cvt_pk_bf16_f32 v15, v16, v17
	ds_read2_b32 v[16:17], v49 offset0:140 offset1:173
	s_waitcnt lgkmcnt(0)
	v_cvt_pk_bf16_f32 v16, v16, v17
	ds_read2_b32 v[18:19], v49 offset0:206 offset1:239
	s_waitcnt lgkmcnt(0)
	v_cvt_pk_bf16_f32 v17, v18, v19
	v_lshl_add_u64 v[22:23], v[20:21], 0, v[0:1]
	v_or_b32_e32 v0, s58, v51
	ds_read2_b32 v[18:19], v49 offset0:16 offset1:49
	global_store_dwordx4 v[22:23], v[14:17], off
	v_mul_u32_u24_e32 v0, 0xb00, v0
	v_lshlrev_b32_e32 v0, 1, v0
	s_waitcnt lgkmcnt(0)
	v_cvt_pk_bf16_f32 v14, v18, v19
	ds_read2_b32 v[16:17], v49 offset0:82 offset1:115
	s_waitcnt lgkmcnt(0)
	v_cvt_pk_bf16_f32 v15, v16, v17
	ds_read2_b32 v[16:17], v49 offset0:148 offset1:181
	s_waitcnt lgkmcnt(0)
	v_cvt_pk_bf16_f32 v16, v16, v17
	ds_read2_b32 v[18:19], v49 offset0:214 offset1:247
	s_waitcnt lgkmcnt(0)
	v_cvt_pk_bf16_f32 v17, v18, v19
	v_lshl_add_u64 v[22:23], v[20:21], 0, v[0:1]
	ds_read2_b32 v[18:19], v49 offset0:24 offset1:57
	global_store_dwordx4 v[22:23], v[14:17], off
	v_or_b32_e32 v0, s58, v52
	v_mul_u32_u24_e32 v0, 0xb00, v0
	s_waitcnt lgkmcnt(0)
	v_cvt_pk_bf16_f32 v14, v18, v19
	ds_read2_b32 v[16:17], v49 offset0:90 offset1:123
	s_waitcnt lgkmcnt(0)
	v_cvt_pk_bf16_f32 v15, v16, v17
	ds_read2_b32 v[16:17], v49 offset0:156 offset1:189
	s_waitcnt lgkmcnt(0)
	v_cvt_pk_bf16_f32 v16, v16, v17
	ds_read2_b32 v[18:19], v49 offset0:222 offset1:255
	v_lshlrev_b32_e32 v0, 1, v0
	s_waitcnt lgkmcnt(0)
	v_cvt_pk_bf16_f32 v17, v18, v19
	v_lshl_add_u64 v[18:19], v[20:21], 0, v[0:1]
	global_store_dwordx4 v[18:19], v[14:17], off
	s_waitcnt lgkmcnt(0)
	s_mov_b64 s[56:57], 0
.LBB0_122:
	s_andn2_b64 vcc, exec, s[56:57]
	s_cbranch_vccnz .LBB0_126
	s_add_i32 s50, s4, 0xfe00
	s_and_b32 s51, s50, 0xffff
	s_mul_i32 s51, s51, 0xba2f
	s_lshr_b32 s51, s51, 23
	s_mul_i32 s54, s51, 0xb0
	s_sub_i32 s50, s50, s54
	s_and_b32 s50, s50, 0xffff
	s_lshl_b32 s56, s50, 5
	s_lshl_b32 s50, s50, 4
	s_and_b32 s54, s56, 0xe0
	s_and_b32 s50, s50, 0xf80
	s_or_b32 s57, s50, s54
	s_add_i32 s50, s50, s54
	s_addk_i32 s50, 0xa80
	s_cmpk_lt_u32 s54, 0x80
	s_cselect_b32 s50, s57, s50
	s_lshl_b32 s57, s51, 6
	v_or_b32_e32 v0, s57, v46
	s_lshl_b32 s54, s50, 2
	v_lshl_add_u64 v[38:39], v[6:7], 0, s[54:55]
	v_or_b32_e32 v16, 2, v0
	v_or_b32_e32 v18, 4, v0
	v_or_b32_e32 v20, 6, v0
	v_or_b32_e32 v22, 8, v0
	v_or_b32_e32 v24, 10, v0
	v_or_b32_e32 v26, 12, v0
	v_or_b32_e32 v28, 14, v0
	v_mad_u64_u32 v[14:15], s[58:59], v0, s63, v[38:39]
	v_mad_u64_u32 v[16:17], s[58:59], v16, s63, v[38:39]
	v_mad_u64_u32 v[18:19], s[58:59], v18, s63, v[38:39]
	v_mad_u64_u32 v[20:21], s[58:59], v20, s63, v[38:39]
	v_mad_u64_u32 v[22:23], s[58:59], v22, s63, v[38:39]
	v_mad_u64_u32 v[24:25], s[58:59], v24, s63, v[38:39]
	v_mad_u64_u32 v[26:27], s[58:59], v26, s63, v[38:39]
	v_mad_u64_u32 v[28:29], s[58:59], v28, s63, v[38:39]
	global_load_dword v14, v[14:15], off nt
	s_nop 0
	global_load_dword v15, v[16:17], off nt
	s_nop 0
	global_load_dword v16, v[18:19], off nt
	global_load_dword v17, v[20:21], off nt
	s_nop 0
	global_load_dword v18, v[22:23], off nt
	global_load_dword v19, v[24:25], off nt
	global_load_dword v20, v[26:27], off nt
	global_load_dword v21, v[28:29], off nt
	v_or_b32_e32 v22, 16, v0
	v_or_b32_e32 v24, 18, v0
	v_or_b32_e32 v26, 20, v0
	v_or_b32_e32 v28, 22, v0
	v_or_b32_e32 v30, 24, v0
	v_or_b32_e32 v32, 26, v0
	v_or_b32_e32 v34, 28, v0
	v_or_b32_e32 v36, 30, v0
	v_mad_u64_u32 v[22:23], s[58:59], v22, s63, v[38:39]
	v_mad_u64_u32 v[24:25], s[58:59], v24, s63, v[38:39]
	v_mad_u64_u32 v[26:27], s[58:59], v26, s63, v[38:39]
	v_mad_u64_u32 v[28:29], s[58:59], v28, s63, v[38:39]
	v_mad_u64_u32 v[30:31], s[58:59], v30, s63, v[38:39]
	v_mad_u64_u32 v[32:33], s[58:59], v32, s63, v[38:39]
	v_mad_u64_u32 v[34:35], s[58:59], v34, s63, v[38:39]
	v_mad_u64_u32 v[36:37], s[58:59], v36, s63, v[38:39]
	global_load_dword v22, v[22:23], off nt
	s_nop 0
	global_load_dword v23, v[24:25], off nt
	s_nop 0
	global_load_dword v24, v[26:27], off nt
	global_load_dword v25, v[28:29], off nt
	s_nop 0
	global_load_dword v26, v[30:31], off nt
	global_load_dword v27, v[32:33], off nt
	global_load_dword v28, v[34:35], off nt
	global_load_dword v29, v[36:37], off nt
	v_or_b32_e32 v30, 32, v0
	v_or_b32_e32 v32, 34, v0
	v_or_b32_e32 v34, 36, v0
	v_or_b32_e32 v36, 38, v0
	v_or_b32_e32 v40, 40, v0
	v_or_b32_e32 v42, 42, v0
	v_or_b32_e32 v44, 44, v0
	v_mad_u64_u32 v[30:31], s[58:59], v30, s63, v[38:39]
	v_mad_u64_u32 v[32:33], s[58:59], v32, s63, v[38:39]
	v_mad_u64_u32 v[34:35], s[58:59], v34, s63, v[38:39]
	v_mad_u64_u32 v[36:37], s[58:59], v36, s63, v[38:39]
	v_mad_u64_u32 v[40:41], s[58:59], v40, s63, v[38:39]
	v_mad_u64_u32 v[42:43], s[58:59], v42, s63, v[38:39]
	v_mad_u64_u32 v[44:45], s[58:59], v44, s63, v[38:39]
	v_or_b32_e32 v60, 46, v0
	v_mad_u64_u32 v[60:61], s[58:59], v60, s63, v[38:39]
	global_load_dword v30, v[30:31], off nt
	s_nop 0
	global_load_dword v31, v[32:33], off nt
	s_nop 0
	global_load_dword v32, v[34:35], off nt
	global_load_dword v33, v[36:37], off nt
	s_nop 0
	global_load_dword v34, v[40:41], off nt
	global_load_dword v35, v[42:43], off nt
	global_load_dword v36, v[44:45], off nt
	global_load_dword v37, v[60:61], off nt
	v_or_b32_e32 v40, 48, v0
	v_or_b32_e32 v42, 50, v0
	v_or_b32_e32 v44, 52, v0
	v_mad_u64_u32 v[40:41], s[58:59], v40, s63, v[38:39]
	v_mad_u64_u32 v[42:43], s[58:59], v42, s63, v[38:39]
	v_mad_u64_u32 v[44:45], s[58:59], v44, s63, v[38:39]
	v_or_b32_e32 v60, 54, v0
	v_or_b32_e32 v62, 56, v0
	v_or_b32_e32 v64, 58, v0
	v_or_b32_e32 v66, 60, v0
	v_or_b32_e32 v68, 62, v0
	v_mad_u64_u32 v[60:61], s[58:59], v60, s63, v[38:39]
	v_mad_u64_u32 v[62:63], s[58:59], v62, s63, v[38:39]
	v_mad_u64_u32 v[64:65], s[58:59], v64, s63, v[38:39]
	v_mad_u64_u32 v[66:67], s[58:59], v66, s63, v[38:39]
	v_mad_u64_u32 v[68:69], s[58:59], v68, s63, v[38:39]
	global_load_dword v38, v[40:41], off nt
	global_load_dword v39, v[42:43], off nt
	s_nop 0
	global_load_dword v40, v[44:45], off nt
	global_load_dword v41, v[60:61], off nt
	s_nop 0
	global_load_dword v44, v[62:63], off nt
	global_load_dword v45, v[64:65], off nt
	global_load_dword v42, v[66:67], off nt
	global_load_dword v43, v[68:69], off nt
	s_and_b64 vcc, exec, s[6:7]
	s_cbranch_vccnz .LBB0_125
	v_lshlrev_b32_e32 v0, 2, v0
	global_load_dword v60, v0, s[36:37] nt
	global_load_dword v61, v0, s[36:37] offset:8 nt
	global_load_dword v62, v0, s[36:37] offset:16 nt
	global_load_dword v63, v0, s[36:37] offset:24 nt
	global_load_dword v64, v0, s[36:37] offset:32 nt
	global_load_dword v65, v0, s[36:37] offset:40 nt
	global_load_dword v66, v0, s[36:37] offset:48 nt
	global_load_dword v67, v0, s[36:37] offset:56 nt
	global_load_dword v68, v0, s[36:37] offset:64 nt
	global_load_dword v69, v0, s[36:37] offset:72 nt
	global_load_dword v70, v0, s[36:37] offset:80 nt
	global_load_dword v71, v0, s[36:37] offset:88 nt
	global_load_dword v72, v0, s[36:37] offset:96 nt
	global_load_dword v73, v0, s[36:37] offset:104 nt
	global_load_dword v74, v0, s[36:37] offset:112 nt
	global_load_dword v75, v0, s[36:37] offset:120 nt
	global_load_dword v76, v0, s[36:37] offset:128 nt
	global_load_dword v77, v0, s[36:37] offset:136 nt
	global_load_dword v78, v0, s[36:37] offset:144 nt
	global_load_dword v79, v0, s[36:37] offset:152 nt
	global_load_dword v80, v0, s[36:37] offset:160 nt
	global_load_dword v81, v0, s[36:37] offset:168 nt
	global_load_dword v82, v0, s[36:37] offset:176 nt
	global_load_dword v83, v0, s[36:37] offset:184 nt
	global_load_dword v84, v0, s[36:37] offset:192 nt
	global_load_dword v85, v0, s[36:37] offset:200 nt
	global_load_dword v86, v0, s[36:37] offset:208 nt
	global_load_dword v87, v0, s[36:37] offset:216 nt
	global_load_dword v88, v0, s[36:37] offset:224 nt
	global_load_dword v89, v0, s[36:37] offset:232 nt
	global_load_dword v90, v0, s[36:37] offset:240 nt
	global_load_dword v91, v0, s[36:37] offset:248 nt
	s_waitcnt vmcnt(0)
	v_pk_mul_f32 v[14:15], v[14:15], v[60:61]
	v_pk_mul_f32 v[16:17], v[16:17], v[62:63]
	v_pk_mul_f32 v[18:19], v[18:19], v[64:65]
	v_pk_mul_f32 v[20:21], v[20:21], v[66:67]
	v_pk_mul_f32 v[22:23], v[22:23], v[68:69]
	v_pk_mul_f32 v[24:25], v[24:25], v[70:71]
	v_pk_mul_f32 v[26:27], v[26:27], v[72:73]
	v_pk_mul_f32 v[28:29], v[28:29], v[74:75]
	v_pk_mul_f32 v[30:31], v[30:31], v[76:77]
	v_pk_mul_f32 v[32:33], v[32:33], v[78:79]
	v_pk_mul_f32 v[34:35], v[34:35], v[80:81]
	v_pk_mul_f32 v[36:37], v[36:37], v[82:83]
	v_pk_mul_f32 v[38:39], v[38:39], v[84:85]
	v_pk_mul_f32 v[40:41], v[40:41], v[86:87]
	v_pk_mul_f32 v[44:45], v[44:45], v[88:89]
	v_pk_mul_f32 v[42:43], v[42:43], v[90:91]

.LBB0_127:
	s_andn2_b64 vcc, exec, s[56:57]
	s_cbranch_vccnz .LBB0_118
	s_ashr_i32 s50, s4, 31
	s_lshr_b32 s50, s50, 27
	s_add_i32 s50, s4, s50
	s_ashr_i32 s50, s50, 5
	s_lshl_b32 s58, s50, 6
	s_lshl_b32 s50, s50, 10
	v_or_b32_e32 v14, s58, v46
	s_sub_i32 s56, s60, s50
	v_or_b32_e32 v20, 2, v14
	v_or_b32_e32 v22, 4, v14
	v_or_b32_e32 v24, 6, v14
	v_or_b32_e32 v26, 8, v14
	v_or_b32_e32 v28, 10, v14
	v_or_b32_e32 v30, 12, v14
	v_or_b32_e32 v32, 14, v14
	s_ashr_i32 s57, s56, 31
	v_ashrrev_i32_e32 v15, 31, v14
	v_ashrrev_i32_e32 v21, 31, v20
	v_ashrrev_i32_e32 v23, 31, v22
	v_ashrrev_i32_e32 v25, 31, v24
	v_ashrrev_i32_e32 v27, 31, v26
	v_ashrrev_i32_e32 v29, 31, v28
	v_ashrrev_i32_e32 v31, 31, v30
	v_ashrrev_i32_e32 v33, 31, v32
	v_lshl_add_u64 v[16:17], s[56:57], 2, v[10:11]
	v_lshlrev_b64 v[18:19], 12, v[14:15]
	v_lshlrev_b64 v[20:21], 12, v[20:21]
	v_lshlrev_b64 v[22:23], 12, v[22:23]
	v_lshlrev_b64 v[24:25], 12, v[24:25]
	v_lshlrev_b64 v[26:27], 12, v[26:27]
	v_lshlrev_b64 v[28:29], 12, v[28:29]
	v_lshlrev_b64 v[30:31], 12, v[30:31]
	v_lshlrev_b64 v[32:33], 12, v[32:33]
	v_lshl_add_u64 v[18:19], v[16:17], 0, v[18:19]
	v_lshl_add_u64 v[20:21], v[16:17], 0, v[20:21]
	v_lshl_add_u64 v[22:23], v[16:17], 0, v[22:23]
	v_lshl_add_u64 v[24:25], v[16:17], 0, v[24:25]
	v_lshl_add_u64 v[26:27], v[16:17], 0, v[26:27]
	v_lshl_add_u64 v[28:29], v[16:17], 0, v[28:29]
	v_lshl_add_u64 v[30:31], v[16:17], 0, v[30:31]
	v_lshl_add_u64 v[32:33], v[16:17], 0, v[32:33]
	global_load_dword v0, v[18:19], off nt
	global_load_dword v34, v[20:21], off nt
	global_load_dword v35, v[22:23], off nt
	global_load_dword v36, v[24:25], off nt
	global_load_dword v37, v[26:27], off nt
	global_load_dword v38, v[28:29], off nt
	global_load_dword v39, v[30:31], off nt
	global_load_dword v40, v[32:33], off nt
	v_or_b32_e32 v18, 16, v14
	v_or_b32_e32 v20, 18, v14
	v_or_b32_e32 v22, 20, v14
	v_or_b32_e32 v24, 22, v14
	v_or_b32_e32 v26, 24, v14
	v_or_b32_e32 v28, 26, v14
	v_or_b32_e32 v30, 28, v14
	v_or_b32_e32 v32, 30, v14
	v_ashrrev_i32_e32 v19, 31, v18
	v_ashrrev_i32_e32 v21, 31, v20
	v_ashrrev_i32_e32 v23, 31, v22
	v_ashrrev_i32_e32 v25, 31, v24
	v_ashrrev_i32_e32 v27, 31, v26
	v_ashrrev_i32_e32 v29, 31, v28
	v_ashrrev_i32_e32 v31, 31, v30
	v_ashrrev_i32_e32 v33, 31, v32
	v_lshlrev_b64 v[18:19], 12, v[18:19]
	v_lshlrev_b64 v[20:21], 12, v[20:21]
	v_lshlrev_b64 v[22:23], 12, v[22:23]
	v_lshlrev_b64 v[24:25], 12, v[24:25]
	v_lshlrev_b64 v[26:27], 12, v[26:27]
	v_lshlrev_b64 v[28:29], 12, v[28:29]
	v_lshlrev_b64 v[30:31], 12, v[30:31]
	v_lshlrev_b64 v[32:33], 12, v[32:33]
	v_lshl_add_u64 v[18:19], v[16:17], 0, v[18:19]
	v_lshl_add_u64 v[20:21], v[16:17], 0, v[20:21]
	v_lshl_add_u64 v[22:23], v[16:17], 0, v[22:23]
	v_lshl_add_u64 v[24:25], v[16:17], 0, v[24:25]
	v_lshl_add_u64 v[26:27], v[16:17], 0, v[26:27]
	v_lshl_add_u64 v[28:29], v[16:17], 0, v[28:29]
	v_lshl_add_u64 v[30:31], v[16:17], 0, v[30:31]
	v_lshl_add_u64 v[32:33], v[16:17], 0, v[32:33]
	global_load_dword v41, v[18:19], off nt
	global_load_dword v42, v[20:21], off nt
	global_load_dword v43, v[22:23], off nt
	global_load_dword v44, v[24:25], off nt
	global_load_dword v45, v[26:27], off nt
	global_load_dword v60, v[28:29], off nt
	global_load_dword v61, v[30:31], off nt
	global_load_dword v62, v[32:33], off nt
	v_or_b32_e32 v18, 32, v14
	v_or_b32_e32 v20, 34, v14
	v_or_b32_e32 v22, 36, v14
	v_or_b32_e32 v24, 38, v14
	v_or_b32_e32 v26, 40, v14
	v_or_b32_e32 v28, 42, v14
	v_or_b32_e32 v30, 44, v14
	v_or_b32_e32 v32, 46, v14
	v_ashrrev_i32_e32 v19, 31, v18
	v_ashrrev_i32_e32 v21, 31, v20
	v_ashrrev_i32_e32 v23, 31, v22
	v_ashrrev_i32_e32 v25, 31, v24
	v_ashrrev_i32_e32 v27, 31, v26
	v_ashrrev_i32_e32 v29, 31, v28
	v_ashrrev_i32_e32 v31, 31, v30
	v_ashrrev_i32_e32 v33, 31, v32
	v_lshlrev_b64 v[18:19], 12, v[18:19]
	v_lshlrev_b64 v[20:21], 12, v[20:21]
	v_lshlrev_b64 v[22:23], 12, v[22:23]
	v_lshlrev_b64 v[24:25], 12, v[24:25]
	v_lshlrev_b64 v[26:27], 12, v[26:27]
	v_lshlrev_b64 v[28:29], 12, v[28:29]
	v_lshlrev_b64 v[30:31], 12, v[30:31]
	v_lshlrev_b64 v[32:33], 12, v[32:33]
	v_lshl_add_u64 v[18:19], v[16:17], 0, v[18:19]
	v_lshl_add_u64 v[20:21], v[16:17], 0, v[20:21]
	v_lshl_add_u64 v[22:23], v[16:17], 0, v[22:23]
	v_lshl_add_u64 v[24:25], v[16:17], 0, v[24:25]
	v_lshl_add_u64 v[26:27], v[16:17], 0, v[26:27]
	v_lshl_add_u64 v[28:29], v[16:17], 0, v[28:29]
	v_lshl_add_u64 v[30:31], v[16:17], 0, v[30:31]
	v_lshl_add_u64 v[32:33], v[16:17], 0, v[32:33]
	global_load_dword v63, v[18:19], off nt
	global_load_dword v64, v[20:21], off nt
	global_load_dword v65, v[22:23], off nt
	global_load_dword v66, v[24:25], off nt
	global_load_dword v67, v[26:27], off nt
	global_load_dword v68, v[28:29], off nt
	global_load_dword v69, v[30:31], off nt
	s_nop 0
	global_load_dword v32, v[32:33], off nt
	v_or_b32_e32 v18, 48, v14
	v_or_b32_e32 v20, 50, v14
	v_or_b32_e32 v22, 52, v14
	v_or_b32_e32 v24, 54, v14
	v_or_b32_e32 v26, 56, v14
	v_or_b32_e32 v28, 58, v14
	v_or_b32_e32 v30, 60, v14
	v_or_b32_e32 v14, 62, v14
	v_ashrrev_i32_e32 v19, 31, v18
	v_ashrrev_i32_e32 v21, 31, v20
	v_ashrrev_i32_e32 v23, 31, v22
	v_ashrrev_i32_e32 v15, 31, v14
	v_lshlrev_b64 v[18:19], 12, v[18:19]
	v_lshlrev_b64 v[20:21], 12, v[20:21]
	v_lshlrev_b64 v[22:23], 12, v[22:23]
	v_ashrrev_i32_e32 v25, 31, v24
	v_ashrrev_i32_e32 v27, 31, v26
	v_ashrrev_i32_e32 v29, 31, v28
	v_ashrrev_i32_e32 v31, 31, v30
	v_lshlrev_b64 v[14:15], 12, v[14:15]
	v_lshl_add_u64 v[18:19], v[16:17], 0, v[18:19]
	v_lshl_add_u64 v[20:21], v[16:17], 0, v[20:21]
	v_lshl_add_u64 v[22:23], v[16:17], 0, v[22:23]
	v_lshlrev_b64 v[24:25], 12, v[24:25]
	v_lshlrev_b64 v[26:27], 12, v[26:27]
	v_lshlrev_b64 v[28:29], 12, v[28:29]
	v_lshlrev_b64 v[30:31], 12, v[30:31]
	v_lshl_add_u64 v[14:15], v[16:17], 0, v[14:15]
	v_lshl_add_u64 v[24:25], v[16:17], 0, v[24:25]
	v_lshl_add_u64 v[26:27], v[16:17], 0, v[26:27]
	v_lshl_add_u64 v[28:29], v[16:17], 0, v[28:29]
	v_lshl_add_u64 v[30:31], v[16:17], 0, v[30:31]
	global_load_dword v16, v[18:19], off nt
	global_load_dword v17, v[20:21], off nt
	s_nop 0
	global_load_dword v18, v[22:23], off nt
	global_load_dword v19, v[24:25], off nt
	global_load_dword v20, v[26:27], off nt
	global_load_dword v21, v[28:29], off nt
	s_nop 0
	global_load_dword v22, v[30:31], off nt
	s_nop 0
	global_load_dword v14, v[14:15], off nt
	s_waitcnt vmcnt(0)
	ds_write2_b32 v47, v0, v34 offset1:66
	ds_write2_b32 v47, v35, v36 offset0:132 offset1:198
	ds_write2_b32 v53, v37, v38 offset0:8 offset1:74
	ds_write2_b32 v53, v39, v40 offset0:140 offset1:206
	ds_write2_b32 v54, v41, v42 offset0:16 offset1:82
	ds_write2_b32 v54, v43, v44 offset0:148 offset1:214
	ds_write2_b32 v55, v45, v60 offset0:24 offset1:90
	ds_write2_b32 v55, v61, v62 offset0:156 offset1:222
	ds_write2_b32 v56, v63, v64 offset0:32 offset1:98
	ds_write2_b32 v56, v65, v66 offset0:164 offset1:230
	ds_write2_b32 v57, v67, v68 offset0:40 offset1:106
	ds_write2_b32 v57, v69, v32 offset0:172 offset1:238
	ds_write2_b32 v58, v16, v17 offset0:48 offset1:114
	ds_write2_b32 v58, v18, v19 offset0:180 offset1:246
	ds_write2_b32 v59, v20, v21 offset0:56 offset1:122
	ds_write2_b32 v59, v22, v14 offset0:188 offset1:254
	s_waitcnt lgkmcnt(0)
	ds_read2_b32 v[14:15], v49 offset1:33
	s_waitcnt lgkmcnt(0)
	v_cvt_pk_bf16_f32 v14, v14, v15
	ds_read2_b32 v[16:17], v49 offset0:66 offset1:99
	s_waitcnt lgkmcnt(0)
	v_cvt_pk_bf16_f32 v15, v16, v17
	ds_read2_b32 v[16:17], v49 offset0:132 offset1:165
	s_waitcnt lgkmcnt(0)
	v_cvt_pk_bf16_f32 v16, v16, v17
	ds_read2_b32 v[18:19], v49 offset0:198 offset1:231
	s_waitcnt lgkmcnt(0)
	v_cvt_pk_bf16_f32 v17, v18, v19
	v_add_u32_e32 v18, s56, v48
	s_ashr_i32 s59, s58, 31
	v_ashrrev_i32_e32 v19, 31, v18
	v_lshl_add_u64 v[20:21], s[58:59], 1, v[12:13]
	v_lshlrev_b64 v[24:25], 11, v[18:19]
	v_lshl_add_u64 v[24:25], v[20:21], 0, v[24:25]
	ds_read2_b32 v[22:23], v49 offset0:8 offset1:41
	global_store_dwordx4 v[24:25], v[14:17], off
	s_waitcnt lgkmcnt(0)
	s_nop 0
	v_cvt_pk_bf16_f32 v14, v22, v23
	ds_read2_b32 v[16:17], v49 offset0:74 offset1:107
	s_waitcnt lgkmcnt(0)
	v_cvt_pk_bf16_f32 v15, v16, v17
	ds_read2_b32 v[16:17], v49 offset0:140 offset1:173
	s_waitcnt lgkmcnt(0)
	v_cvt_pk_bf16_f32 v16, v16, v17
	ds_read2_b32 v[22:23], v49 offset0:206 offset1:239
	s_waitcnt lgkmcnt(0)
	v_cvt_pk_bf16_f32 v17, v22, v23
	v_add_u32_e32 v22, 8, v18
	v_ashrrev_i32_e32 v23, 31, v22
	v_lshlrev_b64 v[22:23], 11, v[22:23]
	v_lshl_add_u64 v[22:23], v[20:21], 0, v[22:23]
	ds_read2_b32 v[24:25], v49 offset0:16 offset1:49
	global_store_dwordx4 v[22:23], v[14:17], off
	s_waitcnt lgkmcnt(0)
	s_nop 0
	v_cvt_pk_bf16_f32 v14, v24, v25
	ds_read2_b32 v[16:17], v49 offset0:82 offset1:115
	s_waitcnt lgkmcnt(0)
	v_cvt_pk_bf16_f32 v15, v16, v17
	ds_read2_b32 v[16:17], v49 offset0:148 offset1:181
	s_waitcnt lgkmcnt(0)
	v_cvt_pk_bf16_f32 v16, v16, v17
	ds_read2_b32 v[22:23], v49 offset0:214 offset1:247
	s_waitcnt lgkmcnt(0)
	v_cvt_pk_bf16_f32 v17, v22, v23
	v_add_u32_e32 v22, 16, v18
	v_ashrrev_i32_e32 v23, 31, v22
	v_lshlrev_b64 v[22:23], 11, v[22:23]
	v_add_u32_e32 v18, 24, v18
	v_lshl_add_u64 v[22:23], v[20:21], 0, v[22:23]
	v_ashrrev_i32_e32 v19, 31, v18
	ds_read2_b32 v[24:25], v49 offset0:24 offset1:57
	global_store_dwordx4 v[22:23], v[14:17], off
	v_lshlrev_b64 v[18:19], 11, v[18:19]
	v_lshl_add_u64 v[18:19], v[20:21], 0, v[18:19]
	s_waitcnt lgkmcnt(0)
	v_cvt_pk_bf16_f32 v14, v24, v25
	ds_read2_b32 v[16:17], v49 offset0:90 offset1:123
	s_waitcnt lgkmcnt(0)
	v_cvt_pk_bf16_f32 v15, v16, v17
	ds_read2_b32 v[16:17], v49 offset0:156 offset1:189
	s_waitcnt lgkmcnt(0)
	v_cvt_pk_bf16_f32 v16, v16, v17
	ds_read2_b32 v[22:23], v49 offset0:222 offset1:255
	s_waitcnt lgkmcnt(0)
	v_cvt_pk_bf16_f32 v17, v22, v23
	global_store_dwordx4 v[18:19], v[14:17], off
	s_waitcnt lgkmcnt(0)
	s_branch .LBB0_118

.LBB0_135:
	s_cmpk_gt_i32 s3, 0x1ff
	s_mov_b64 s[26:27], -1
	s_cbranch_scc0 .LBB0_143
	s_cmpk_gt_u32 s3, 0xcff
	s_cbranch_scc0 .LBB0_138
	s_and_b32 s16, s43, 0x7fffffc0
	s_add_i32 s26, s16, 0xffffe600
	s_and_b32 s38, s5, 0x3e0
	v_or_b32_e32 v0, s26, v46
	s_lshl_b32 s16, s38, 2
	v_or_b32_e32 v18, 2, v0
	v_mov_b32_e32 v19, v1
	v_or_b32_e32 v20, 4, v0
	v_mov_b32_e32 v21, v1
	v_or_b32_e32 v22, 6, v0
	v_mov_b32_e32 v23, v1
	v_or_b32_e32 v24, 8, v0
	v_mov_b32_e32 v25, v1
	v_or_b32_e32 v26, 10, v0
	v_mov_b32_e32 v27, v1
	v_or_b32_e32 v28, 12, v0
	v_mov_b32_e32 v29, v1
	v_lshl_add_u64 v[14:15], v[2:3], 0, s[16:17]
	v_lshlrev_b64 v[16:17], 12, v[0:1]
	v_lshlrev_b64 v[18:19], 12, v[18:19]
	v_lshlrev_b64 v[20:21], 12, v[20:21]
	v_lshlrev_b64 v[22:23], 12, v[22:23]
	v_lshlrev_b64 v[24:25], 12, v[24:25]
	v_lshlrev_b64 v[26:27], 12, v[26:27]
	v_lshlrev_b64 v[28:29], 12, v[28:29]
	v_or_b32_e32 v30, 14, v0
	v_mov_b32_e32 v31, v1
	v_lshl_add_u64 v[16:17], v[14:15], 0, v[16:17]
	v_lshl_add_u64 v[18:19], v[14:15], 0, v[18:19]
	v_lshl_add_u64 v[20:21], v[14:15], 0, v[20:21]
	v_lshl_add_u64 v[22:23], v[14:15], 0, v[22:23]
	v_lshl_add_u64 v[24:25], v[14:15], 0, v[24:25]
	v_lshl_add_u64 v[26:27], v[14:15], 0, v[26:27]
	v_lshl_add_u64 v[28:29], v[14:15], 0, v[28:29]
	v_lshlrev_b64 v[30:31], 12, v[30:31]
	v_lshl_add_u64 v[30:31], v[14:15], 0, v[30:31]
	global_load_dword v32, v[16:17], off nt
	global_load_dword v33, v[18:19], off nt
	global_load_dword v34, v[20:21], off nt
	global_load_dword v35, v[22:23], off nt
	global_load_dword v36, v[24:25], off nt
	global_load_dword v37, v[26:27], off nt
	global_load_dword v38, v[28:29], off nt
	global_load_dword v39, v[30:31], off nt
	v_or_b32_e32 v16, 16, v0
	v_mov_b32_e32 v17, v1
	v_or_b32_e32 v18, 18, v0
	v_mov_b32_e32 v19, v1
	v_or_b32_e32 v20, 20, v0
	v_mov_b32_e32 v21, v1
	v_or_b32_e32 v22, 22, v0
	v_mov_b32_e32 v23, v1
	v_or_b32_e32 v24, 24, v0
	v_mov_b32_e32 v25, v1
	v_or_b32_e32 v26, 26, v0
	v_mov_b32_e32 v27, v1
	v_or_b32_e32 v28, 28, v0
	v_mov_b32_e32 v29, v1
	v_lshlrev_b64 v[16:17], 12, v[16:17]
	v_lshlrev_b64 v[18:19], 12, v[18:19]
	v_lshlrev_b64 v[20:21], 12, v[20:21]
	v_lshlrev_b64 v[22:23], 12, v[22:23]
	v_lshlrev_b64 v[24:25], 12, v[24:25]
	v_lshlrev_b64 v[26:27], 12, v[26:27]
	v_lshlrev_b64 v[28:29], 12, v[28:29]
	v_or_b32_e32 v30, 30, v0
	v_mov_b32_e32 v31, v1
	v_lshl_add_u64 v[16:17], v[14:15], 0, v[16:17]
	v_lshl_add_u64 v[18:19], v[14:15], 0, v[18:19]
	v_lshl_add_u64 v[20:21], v[14:15], 0, v[20:21]
	v_lshl_add_u64 v[22:23], v[14:15], 0, v[22:23]
	v_lshl_add_u64 v[24:25], v[14:15], 0, v[24:25]
	v_lshl_add_u64 v[26:27], v[14:15], 0, v[26:27]
	v_lshl_add_u64 v[28:29], v[14:15], 0, v[28:29]
	v_lshlrev_b64 v[30:31], 12, v[30:31]
	v_lshl_add_u64 v[30:31], v[14:15], 0, v[30:31]
	global_load_dword v40, v[16:17], off nt
	global_load_dword v41, v[18:19], off nt
	global_load_dword v42, v[20:21], off nt
	global_load_dword v43, v[22:23], off nt
	global_load_dword v44, v[24:25], off nt
	global_load_dword v45, v[26:27], off nt
	global_load_dword v60, v[28:29], off nt
	global_load_dword v61, v[30:31], off nt
	v_or_b32_e32 v16, 32, v0
	v_mov_b32_e32 v17, v1
	v_or_b32_e32 v18, 34, v0
	v_mov_b32_e32 v19, v1
	v_or_b32_e32 v20, 36, v0
	v_mov_b32_e32 v21, v1
	v_or_b32_e32 v22, 38, v0
	v_mov_b32_e32 v23, v1
	v_or_b32_e32 v24, 40, v0
	v_mov_b32_e32 v25, v1
	v_or_b32_e32 v26, 42, v0
	v_mov_b32_e32 v27, v1
	v_or_b32_e32 v28, 44, v0
	v_mov_b32_e32 v29, v1
	v_lshlrev_b64 v[16:17], 12, v[16:17]
	v_lshlrev_b64 v[18:19], 12, v[18:19]
	v_lshlrev_b64 v[20:21], 12, v[20:21]
	v_lshlrev_b64 v[22:23], 12, v[22:23]
	v_lshlrev_b64 v[24:25], 12, v[24:25]
	v_lshlrev_b64 v[26:27], 12, v[26:27]
	v_lshlrev_b64 v[28:29], 12, v[28:29]
	v_or_b32_e32 v30, 46, v0
	v_mov_b32_e32 v31, v1
	v_lshl_add_u64 v[16:17], v[14:15], 0, v[16:17]
	v_lshl_add_u64 v[18:19], v[14:15], 0, v[18:19]
	v_lshl_add_u64 v[20:21], v[14:15], 0, v[20:21]
	v_lshl_add_u64 v[22:23], v[14:15], 0, v[22:23]
	v_lshl_add_u64 v[24:25], v[14:15], 0, v[24:25]
	v_lshl_add_u64 v[26:27], v[14:15], 0, v[26:27]
	v_lshl_add_u64 v[28:29], v[14:15], 0, v[28:29]
	v_lshlrev_b64 v[30:31], 12, v[30:31]
	v_lshl_add_u64 v[30:31], v[14:15], 0, v[30:31]
	global_load_dword v62, v[16:17], off nt
	global_load_dword v63, v[18:19], off nt
	global_load_dword v64, v[20:21], off nt
	global_load_dword v65, v[22:23], off nt
	global_load_dword v66, v[24:25], off nt
	global_load_dword v67, v[26:27], off nt
	global_load_dword v68, v[28:29], off nt
	global_load_dword v69, v[30:31], off nt
	v_or_b32_e32 v16, 48, v0
	v_mov_b32_e32 v17, v1
	v_or_b32_e32 v18, 50, v0
	v_mov_b32_e32 v19, v1
	v_or_b32_e32 v20, 52, v0
	v_mov_b32_e32 v21, v1
	v_or_b32_e32 v22, 54, v0
	v_mov_b32_e32 v23, v1
	v_or_b32_e32 v24, 56, v0
	v_mov_b32_e32 v25, v1
	v_or_b32_e32 v26, 58, v0
	v_mov_b32_e32 v27, v1
	v_or_b32_e32 v28, 60, v0
	v_mov_b32_e32 v29, v1
	v_or_b32_e32 v0, 62, v0
	v_lshlrev_b64 v[16:17], 12, v[16:17]
	v_lshlrev_b64 v[18:19], 12, v[18:19]
	v_lshlrev_b64 v[20:21], 12, v[20:21]
	v_lshlrev_b64 v[22:23], 12, v[22:23]
	v_lshlrev_b64 v[24:25], 12, v[24:25]
	v_lshlrev_b64 v[26:27], 12, v[26:27]
	v_lshlrev_b64 v[28:29], 12, v[28:29]
	v_lshlrev_b64 v[30:31], 12, v[0:1]
	v_lshl_add_u64 v[16:17], v[14:15], 0, v[16:17]
	v_lshl_add_u64 v[18:19], v[14:15], 0, v[18:19]
	v_lshl_add_u64 v[20:21], v[14:15], 0, v[20:21]
	v_lshl_add_u64 v[22:23], v[14:15], 0, v[22:23]
	v_lshl_add_u64 v[24:25], v[14:15], 0, v[24:25]
	v_lshl_add_u64 v[26:27], v[14:15], 0, v[26:27]
	v_lshl_add_u64 v[28:29], v[14:15], 0, v[28:29]
	v_lshl_add_u64 v[14:15], v[14:15], 0, v[30:31]
	global_load_dword v0, v[16:17], off nt
	s_nop 0
	global_load_dword v16, v[18:19], off nt
	global_load_dword v17, v[20:21], off nt
	s_nop 0
	global_load_dword v18, v[22:23], off nt
	global_load_dword v19, v[24:25], off nt
	global_load_dword v20, v[26:27], off nt
	global_load_dword v21, v[28:29], off nt
	s_nop 0
	global_load_dword v14, v[14:15], off nt
	s_waitcnt vmcnt(0)
	ds_write2_b32 v47, v32, v33 offset1:66
	ds_write2_b32 v47, v34, v35 offset0:132 offset1:198
	ds_write2_b32 v53, v36, v37 offset0:8 offset1:74
	ds_write2_b32 v53, v38, v39 offset0:140 offset1:206
	ds_write2_b32 v54, v40, v41 offset0:16 offset1:82
	ds_write2_b32 v54, v42, v43 offset0:148 offset1:214
	ds_write2_b32 v55, v44, v45 offset0:24 offset1:90
	ds_write2_b32 v55, v60, v61 offset0:156 offset1:222
	ds_write2_b32 v56, v62, v63 offset0:32 offset1:98
	ds_write2_b32 v56, v64, v65 offset0:164 offset1:230
	ds_write2_b32 v57, v66, v67 offset0:40 offset1:106
	ds_write2_b32 v57, v68, v69 offset0:172 offset1:238
	ds_write2_b32 v58, v0, v16 offset0:48 offset1:114
	ds_write2_b32 v58, v17, v18 offset0:180 offset1:246
	ds_write2_b32 v59, v19, v20 offset0:56 offset1:122
	ds_write2_b32 v59, v21, v14 offset0:188 offset1:254
	s_waitcnt lgkmcnt(0)
	ds_read2_b32 v[14:15], v49 offset1:33
	v_or_b32_e32 v0, s38, v48
	s_waitcnt lgkmcnt(0)
	v_cvt_pk_bf16_f32 v14, v14, v15
	ds_read2_b32 v[16:17], v49 offset0:66 offset1:99
	s_mov_b32 s27, s17
	v_mul_u32_u24_e32 v0, 0xb00, v0
	s_waitcnt lgkmcnt(0)
	v_cvt_pk_bf16_f32 v15, v16, v17
	ds_read2_b32 v[16:17], v49 offset0:132 offset1:165
	v_lshl_add_u64 v[20:21], s[26:27], 1, v[4:5]
	v_lshlrev_b32_e32 v0, 1, v0
	s_waitcnt lgkmcnt(0)
	v_cvt_pk_bf16_f32 v16, v16, v17
	ds_read2_b32 v[18:19], v49 offset0:198 offset1:231
	s_waitcnt lgkmcnt(0)
	v_cvt_pk_bf16_f32 v17, v18, v19
	v_lshl_add_u64 v[22:23], v[20:21], 0, v[0:1]
	v_or_b32_e32 v0, s38, v50
	ds_read2_b32 v[18:19], v49 offset0:8 offset1:41
	global_store_dwordx4 v[22:23], v[14:17], off
	v_mul_u32_u24_e32 v0, 0xb00, v0
	v_lshlrev_b32_e32 v0, 1, v0
	s_waitcnt lgkmcnt(0)
	v_cvt_pk_bf16_f32 v14, v18, v19
	ds_read2_b32 v[16:17], v49 offset0:74 offset1:107
	s_waitcnt lgkmcnt(0)
	v_cvt_pk_bf16_f32 v15, v16, v17
	ds_read2_b32 v[16:17], v49 offset0:140 offset1:173
	s_waitcnt lgkmcnt(0)
	v_cvt_pk_bf16_f32 v16, v16, v17
	ds_read2_b32 v[18:19], v49 offset0:206 offset1:239
	s_waitcnt lgkmcnt(0)
	v_cvt_pk_bf16_f32 v17, v18, v19
	v_lshl_add_u64 v[22:23], v[20:21], 0, v[0:1]
	v_or_b32_e32 v0, s38, v51
	ds_read2_b32 v[18:19], v49 offset0:16 offset1:49
	global_store_dwordx4 v[22:23], v[14:17], off
	v_mul_u32_u24_e32 v0, 0xb00, v0
	v_lshlrev_b32_e32 v0, 1, v0
	s_waitcnt lgkmcnt(0)
	v_cvt_pk_bf16_f32 v14, v18, v19
	ds_read2_b32 v[16:17], v49 offset0:82 offset1:115
	s_waitcnt lgkmcnt(0)
	v_cvt_pk_bf16_f32 v15, v16, v17
	ds_read2_b32 v[16:17], v49 offset0:148 offset1:181
	s_waitcnt lgkmcnt(0)
	v_cvt_pk_bf16_f32 v16, v16, v17
	ds_read2_b32 v[18:19], v49 offset0:214 offset1:247
	s_waitcnt lgkmcnt(0)
	v_cvt_pk_bf16_f32 v17, v18, v19
	v_lshl_add_u64 v[22:23], v[20:21], 0, v[0:1]
	ds_read2_b32 v[18:19], v49 offset0:24 offset1:57
	global_store_dwordx4 v[22:23], v[14:17], off
	v_or_b32_e32 v0, s38, v52
	v_mul_u32_u24_e32 v0, 0xb00, v0
	s_waitcnt lgkmcnt(0)
	v_cvt_pk_bf16_f32 v14, v18, v19
	ds_read2_b32 v[16:17], v49 offset0:90 offset1:123
	s_waitcnt lgkmcnt(0)
	v_cvt_pk_bf16_f32 v15, v16, v17
	ds_read2_b32 v[16:17], v49 offset0:156 offset1:189
	s_waitcnt lgkmcnt(0)
	v_cvt_pk_bf16_f32 v16, v16, v17
	ds_read2_b32 v[18:19], v49 offset0:222 offset1:255
	v_lshlrev_b32_e32 v0, 1, v0
	s_waitcnt lgkmcnt(0)
	v_cvt_pk_bf16_f32 v17, v18, v19
	v_lshl_add_u64 v[18:19], v[20:21], 0, v[0:1]
	global_store_dwordx4 v[18:19], v[14:17], off
	s_waitcnt lgkmcnt(0)
	s_mov_b64 s[26:27], 0
.LBB0_138:
	s_andn2_b64 vcc, exec, s[26:27]
	s_cbranch_vccnz .LBB0_142
	s_add_i32 s16, s3, 0xfe00
	s_and_b32 s26, s16, 0xffff
	s_mul_i32 s26, s26, 0xba2f
	s_lshr_b32 s27, s26, 23
	s_mul_i32 s26, s27, 0xb0
	s_sub_i32 s16, s16, s26
	s_and_b32 s16, s16, 0xffff
	s_lshl_b32 s26, s16, 5
	s_lshl_b32 s16, s16, 4
	s_and_b32 s38, s26, 0xe0
	s_and_b32 s16, s16, 0xf80
	s_or_b32 s39, s16, s38
	s_add_i32 s16, s16, s38
	s_addk_i32 s16, 0xa80
	s_cmpk_lt_u32 s38, 0x80
	s_cselect_b32 s16, s39, s16
	s_lshl_b32 s27, s27, 6
	v_or_b32_e32 v0, s27, v46
	s_lshl_b32 s16, s16, 2
	v_lshl_add_u64 v[38:39], v[6:7], 0, s[16:17]
	v_or_b32_e32 v16, 2, v0
	v_or_b32_e32 v18, 4, v0
	v_or_b32_e32 v20, 6, v0
	v_or_b32_e32 v22, 8, v0
	v_or_b32_e32 v24, 10, v0
	v_or_b32_e32 v26, 12, v0
	v_or_b32_e32 v28, 14, v0
	v_mad_u64_u32 v[14:15], s[38:39], v0, s55, v[38:39]
	v_mad_u64_u32 v[16:17], s[38:39], v16, s55, v[38:39]
	v_mad_u64_u32 v[18:19], s[38:39], v18, s55, v[38:39]
	v_mad_u64_u32 v[20:21], s[38:39], v20, s55, v[38:39]
	v_mad_u64_u32 v[22:23], s[38:39], v22, s55, v[38:39]
	v_mad_u64_u32 v[24:25], s[38:39], v24, s55, v[38:39]
	v_mad_u64_u32 v[26:27], s[38:39], v26, s55, v[38:39]
	v_mad_u64_u32 v[28:29], s[38:39], v28, s55, v[38:39]
	global_load_dword v14, v[14:15], off nt
	s_nop 0
	global_load_dword v15, v[16:17], off nt
	s_nop 0
	global_load_dword v16, v[18:19], off nt
	global_load_dword v17, v[20:21], off nt
	s_nop 0
	global_load_dword v18, v[22:23], off nt
	global_load_dword v19, v[24:25], off nt
	global_load_dword v20, v[26:27], off nt
	global_load_dword v21, v[28:29], off nt
	v_or_b32_e32 v22, 16, v0
	v_or_b32_e32 v24, 18, v0
	v_or_b32_e32 v26, 20, v0
	v_or_b32_e32 v28, 22, v0
	v_or_b32_e32 v30, 24, v0
	v_or_b32_e32 v32, 26, v0
	v_or_b32_e32 v34, 28, v0
	v_or_b32_e32 v36, 30, v0
	v_mad_u64_u32 v[22:23], s[38:39], v22, s55, v[38:39]
	v_mad_u64_u32 v[24:25], s[38:39], v24, s55, v[38:39]
	v_mad_u64_u32 v[26:27], s[38:39], v26, s55, v[38:39]
	v_mad_u64_u32 v[28:29], s[38:39], v28, s55, v[38:39]
	v_mad_u64_u32 v[30:31], s[38:39], v30, s55, v[38:39]
	v_mad_u64_u32 v[32:33], s[38:39], v32, s55, v[38:39]
	v_mad_u64_u32 v[34:35], s[38:39], v34, s55, v[38:39]
	v_mad_u64_u32 v[36:37], s[38:39], v36, s55, v[38:39]
	global_load_dword v22, v[22:23], off nt
	s_nop 0
	global_load_dword v23, v[24:25], off nt
	s_nop 0
	global_load_dword v24, v[26:27], off nt
	global_load_dword v25, v[28:29], off nt
	s_nop 0
	global_load_dword v26, v[30:31], off nt
	global_load_dword v27, v[32:33], off nt
	global_load_dword v28, v[34:35], off nt
	global_load_dword v29, v[36:37], off nt
	v_or_b32_e32 v30, 32, v0
	v_or_b32_e32 v32, 34, v0
	v_or_b32_e32 v34, 36, v0
	v_or_b32_e32 v36, 38, v0
	v_or_b32_e32 v40, 40, v0
	v_or_b32_e32 v42, 42, v0
	v_or_b32_e32 v44, 44, v0
	v_mad_u64_u32 v[30:31], s[38:39], v30, s55, v[38:39]
	v_mad_u64_u32 v[32:33], s[38:39], v32, s55, v[38:39]
	v_mad_u64_u32 v[34:35], s[38:39], v34, s55, v[38:39]
	v_mad_u64_u32 v[36:37], s[38:39], v36, s55, v[38:39]
	v_mad_u64_u32 v[40:41], s[38:39], v40, s55, v[38:39]
	v_mad_u64_u32 v[42:43], s[38:39], v42, s55, v[38:39]
	v_mad_u64_u32 v[44:45], s[38:39], v44, s55, v[38:39]
	v_or_b32_e32 v60, 46, v0
	v_mad_u64_u32 v[60:61], s[38:39], v60, s55, v[38:39]
	global_load_dword v30, v[30:31], off nt
	s_nop 0
	global_load_dword v31, v[32:33], off nt
	s_nop 0
	global_load_dword v32, v[34:35], off nt
	global_load_dword v33, v[36:37], off nt
	s_nop 0
	global_load_dword v34, v[40:41], off nt
	global_load_dword v35, v[42:43], off nt
	global_load_dword v36, v[44:45], off nt
	global_load_dword v37, v[60:61], off nt
	v_or_b32_e32 v40, 48, v0
	v_or_b32_e32 v42, 50, v0
	v_or_b32_e32 v44, 52, v0
	v_mad_u64_u32 v[40:41], s[38:39], v40, s55, v[38:39]
	v_mad_u64_u32 v[42:43], s[38:39], v42, s55, v[38:39]
	v_mad_u64_u32 v[44:45], s[38:39], v44, s55, v[38:39]
	v_or_b32_e32 v60, 54, v0
	v_or_b32_e32 v62, 56, v0
	v_or_b32_e32 v64, 58, v0
	v_or_b32_e32 v66, 60, v0
	v_or_b32_e32 v68, 62, v0
	v_mad_u64_u32 v[60:61], s[38:39], v60, s55, v[38:39]
	v_mad_u64_u32 v[62:63], s[38:39], v62, s55, v[38:39]
	v_mad_u64_u32 v[64:65], s[38:39], v64, s55, v[38:39]
	v_mad_u64_u32 v[66:67], s[38:39], v66, s55, v[38:39]
	v_mad_u64_u32 v[68:69], s[38:39], v68, s55, v[38:39]
	global_load_dword v38, v[40:41], off nt
	global_load_dword v39, v[42:43], off nt
	s_nop 0
	global_load_dword v40, v[44:45], off nt
	global_load_dword v41, v[60:61], off nt
	s_nop 0
	global_load_dword v44, v[62:63], off nt
	global_load_dword v45, v[64:65], off nt
	global_load_dword v42, v[66:67], off nt
	global_load_dword v43, v[68:69], off nt
	s_and_b64 vcc, exec, s[6:7]
	s_cbranch_vccnz .LBB0_141
	v_lshlrev_b32_e32 v0, 2, v0
	global_load_dword v60, v0, s[36:37] nt
	global_load_dword v61, v0, s[36:37] offset:8 nt
	global_load_dword v62, v0, s[36:37] offset:16 nt
	global_load_dword v63, v0, s[36:37] offset:24 nt
	global_load_dword v64, v0, s[36:37] offset:32 nt
	global_load_dword v65, v0, s[36:37] offset:40 nt
	global_load_dword v66, v0, s[36:37] offset:48 nt
	global_load_dword v67, v0, s[36:37] offset:56 nt
	global_load_dword v68, v0, s[36:37] offset:64 nt
	global_load_dword v69, v0, s[36:37] offset:72 nt
	global_load_dword v70, v0, s[36:37] offset:80 nt
	global_load_dword v71, v0, s[36:37] offset:88 nt
	global_load_dword v72, v0, s[36:37] offset:96 nt
	global_load_dword v73, v0, s[36:37] offset:104 nt
	global_load_dword v74, v0, s[36:37] offset:112 nt
	global_load_dword v75, v0, s[36:37] offset:120 nt
	global_load_dword v76, v0, s[36:37] offset:128 nt
	global_load_dword v77, v0, s[36:37] offset:136 nt
	global_load_dword v78, v0, s[36:37] offset:144 nt
	global_load_dword v79, v0, s[36:37] offset:152 nt
	global_load_dword v80, v0, s[36:37] offset:160 nt
	global_load_dword v81, v0, s[36:37] offset:168 nt
	global_load_dword v82, v0, s[36:37] offset:176 nt
	global_load_dword v83, v0, s[36:37] offset:184 nt
	global_load_dword v84, v0, s[36:37] offset:192 nt
	global_load_dword v85, v0, s[36:37] offset:200 nt
	global_load_dword v86, v0, s[36:37] offset:208 nt
	global_load_dword v87, v0, s[36:37] offset:216 nt
	global_load_dword v88, v0, s[36:37] offset:224 nt
	global_load_dword v89, v0, s[36:37] offset:232 nt
	global_load_dword v90, v0, s[36:37] offset:240 nt
	global_load_dword v91, v0, s[36:37] offset:248 nt
	s_waitcnt vmcnt(0)
	v_pk_mul_f32 v[14:15], v[14:15], v[60:61]
	v_pk_mul_f32 v[16:17], v[16:17], v[62:63]
	v_pk_mul_f32 v[18:19], v[18:19], v[64:65]
	v_pk_mul_f32 v[20:21], v[20:21], v[66:67]
	v_pk_mul_f32 v[22:23], v[22:23], v[68:69]
	v_pk_mul_f32 v[24:25], v[24:25], v[70:71]
	v_pk_mul_f32 v[26:27], v[26:27], v[72:73]
	v_pk_mul_f32 v[28:29], v[28:29], v[74:75]
	v_pk_mul_f32 v[30:31], v[30:31], v[76:77]
	v_pk_mul_f32 v[32:33], v[32:33], v[78:79]
	v_pk_mul_f32 v[34:35], v[34:35], v[80:81]
	v_pk_mul_f32 v[36:37], v[36:37], v[82:83]
	v_pk_mul_f32 v[38:39], v[38:39], v[84:85]
	v_pk_mul_f32 v[40:41], v[40:41], v[86:87]
	v_pk_mul_f32 v[44:45], v[44:45], v[88:89]
	v_pk_mul_f32 v[42:43], v[42:43], v[90:91]

.LBB0_143:
	s_andn2_b64 vcc, exec, s[26:27]
	s_cbranch_vccnz .LBB0_134
	s_ashr_i32 s16, s3, 31
	s_lshr_b32 s16, s16, 27
	s_add_i32 s16, s3, s16
	s_ashr_i32 s16, s16, 5
	s_lshl_b32 s38, s16, 6
	s_lshl_b32 s16, s16, 10
	v_or_b32_e32 v14, s38, v46
	s_sub_i32 s26, s5, s16
	v_or_b32_e32 v20, 2, v14
	v_or_b32_e32 v22, 4, v14
	v_or_b32_e32 v24, 6, v14
	v_or_b32_e32 v26, 8, v14
	v_or_b32_e32 v28, 10, v14
	v_or_b32_e32 v30, 12, v14
	v_or_b32_e32 v32, 14, v14
	s_ashr_i32 s27, s26, 31
	v_ashrrev_i32_e32 v15, 31, v14
	v_ashrrev_i32_e32 v21, 31, v20
	v_ashrrev_i32_e32 v23, 31, v22
	v_ashrrev_i32_e32 v25, 31, v24
	v_ashrrev_i32_e32 v27, 31, v26
	v_ashrrev_i32_e32 v29, 31, v28
	v_ashrrev_i32_e32 v31, 31, v30
	v_ashrrev_i32_e32 v33, 31, v32
	v_lshl_add_u64 v[16:17], s[26:27], 2, v[10:11]
	v_lshlrev_b64 v[18:19], 12, v[14:15]
	v_lshlrev_b64 v[20:21], 12, v[20:21]
	v_lshlrev_b64 v[22:23], 12, v[22:23]
	v_lshlrev_b64 v[24:25], 12, v[24:25]
	v_lshlrev_b64 v[26:27], 12, v[26:27]
	v_lshlrev_b64 v[28:29], 12, v[28:29]
	v_lshlrev_b64 v[30:31], 12, v[30:31]
	v_lshlrev_b64 v[32:33], 12, v[32:33]
	v_lshl_add_u64 v[18:19], v[16:17], 0, v[18:19]
	v_lshl_add_u64 v[20:21], v[16:17], 0, v[20:21]
	v_lshl_add_u64 v[22:23], v[16:17], 0, v[22:23]
	v_lshl_add_u64 v[24:25], v[16:17], 0, v[24:25]
	v_lshl_add_u64 v[26:27], v[16:17], 0, v[26:27]
	v_lshl_add_u64 v[28:29], v[16:17], 0, v[28:29]
	v_lshl_add_u64 v[30:31], v[16:17], 0, v[30:31]
	v_lshl_add_u64 v[32:33], v[16:17], 0, v[32:33]
	global_load_dword v0, v[18:19], off nt
	global_load_dword v34, v[20:21], off nt
	global_load_dword v35, v[22:23], off nt
	global_load_dword v36, v[24:25], off nt
	global_load_dword v37, v[26:27], off nt
	global_load_dword v38, v[28:29], off nt
	global_load_dword v39, v[30:31], off nt
	global_load_dword v40, v[32:33], off nt
	v_or_b32_e32 v18, 16, v14
	v_or_b32_e32 v20, 18, v14
	v_or_b32_e32 v22, 20, v14
	v_or_b32_e32 v24, 22, v14
	v_or_b32_e32 v26, 24, v14
	v_or_b32_e32 v28, 26, v14
	v_or_b32_e32 v30, 28, v14
	v_or_b32_e32 v32, 30, v14
	v_ashrrev_i32_e32 v19, 31, v18
	v_ashrrev_i32_e32 v21, 31, v20
	v_ashrrev_i32_e32 v23, 31, v22
	v_ashrrev_i32_e32 v25, 31, v24
	v_ashrrev_i32_e32 v27, 31, v26
	v_ashrrev_i32_e32 v29, 31, v28
	v_ashrrev_i32_e32 v31, 31, v30
	v_ashrrev_i32_e32 v33, 31, v32
	v_lshlrev_b64 v[18:19], 12, v[18:19]
	v_lshlrev_b64 v[20:21], 12, v[20:21]
	v_lshlrev_b64 v[22:23], 12, v[22:23]
	v_lshlrev_b64 v[24:25], 12, v[24:25]
	v_lshlrev_b64 v[26:27], 12, v[26:27]
	v_lshlrev_b64 v[28:29], 12, v[28:29]
	v_lshlrev_b64 v[30:31], 12, v[30:31]
	v_lshlrev_b64 v[32:33], 12, v[32:33]
	v_lshl_add_u64 v[18:19], v[16:17], 0, v[18:19]
	v_lshl_add_u64 v[20:21], v[16:17], 0, v[20:21]
	v_lshl_add_u64 v[22:23], v[16:17], 0, v[22:23]
	v_lshl_add_u64 v[24:25], v[16:17], 0, v[24:25]
	v_lshl_add_u64 v[26:27], v[16:17], 0, v[26:27]
	v_lshl_add_u64 v[28:29], v[16:17], 0, v[28:29]
	v_lshl_add_u64 v[30:31], v[16:17], 0, v[30:31]
	v_lshl_add_u64 v[32:33], v[16:17], 0, v[32:33]
	global_load_dword v41, v[18:19], off nt
	global_load_dword v42, v[20:21], off nt
	global_load_dword v43, v[22:23], off nt
	global_load_dword v44, v[24:25], off nt
	global_load_dword v45, v[26:27], off nt
	global_load_dword v60, v[28:29], off nt
	global_load_dword v61, v[30:31], off nt
	global_load_dword v62, v[32:33], off nt
	v_or_b32_e32 v18, 32, v14
	v_or_b32_e32 v20, 34, v14
	v_or_b32_e32 v22, 36, v14
	v_or_b32_e32 v24, 38, v14
	v_or_b32_e32 v26, 40, v14
	v_or_b32_e32 v28, 42, v14
	v_or_b32_e32 v30, 44, v14
	v_or_b32_e32 v32, 46, v14
	v_ashrrev_i32_e32 v19, 31, v18
	v_ashrrev_i32_e32 v21, 31, v20
	v_ashrrev_i32_e32 v23, 31, v22
	v_ashrrev_i32_e32 v25, 31, v24
	v_ashrrev_i32_e32 v27, 31, v26
	v_ashrrev_i32_e32 v29, 31, v28
	v_ashrrev_i32_e32 v31, 31, v30
	v_ashrrev_i32_e32 v33, 31, v32
	v_lshlrev_b64 v[18:19], 12, v[18:19]
	v_lshlrev_b64 v[20:21], 12, v[20:21]
	v_lshlrev_b64 v[22:23], 12, v[22:23]
	v_lshlrev_b64 v[24:25], 12, v[24:25]
	v_lshlrev_b64 v[26:27], 12, v[26:27]
	v_lshlrev_b64 v[28:29], 12, v[28:29]
	v_lshlrev_b64 v[30:31], 12, v[30:31]
	v_lshlrev_b64 v[32:33], 12, v[32:33]
	v_lshl_add_u64 v[18:19], v[16:17], 0, v[18:19]
	v_lshl_add_u64 v[20:21], v[16:17], 0, v[20:21]
	v_lshl_add_u64 v[22:23], v[16:17], 0, v[22:23]
	v_lshl_add_u64 v[24:25], v[16:17], 0, v[24:25]
	v_lshl_add_u64 v[26:27], v[16:17], 0, v[26:27]
	v_lshl_add_u64 v[28:29], v[16:17], 0, v[28:29]
	v_lshl_add_u64 v[30:31], v[16:17], 0, v[30:31]
	v_lshl_add_u64 v[32:33], v[16:17], 0, v[32:33]
	global_load_dword v63, v[18:19], off nt
	global_load_dword v64, v[20:21], off nt
	global_load_dword v65, v[22:23], off nt
	global_load_dword v66, v[24:25], off nt
	global_load_dword v67, v[26:27], off nt
	global_load_dword v68, v[28:29], off nt
	global_load_dword v69, v[30:31], off nt
	s_nop 0
	global_load_dword v32, v[32:33], off nt
	v_or_b32_e32 v18, 48, v14
	v_or_b32_e32 v20, 50, v14
	v_or_b32_e32 v22, 52, v14
	v_or_b32_e32 v24, 54, v14
	v_or_b32_e32 v26, 56, v14
	v_or_b32_e32 v28, 58, v14
	v_or_b32_e32 v30, 60, v14
	v_or_b32_e32 v14, 62, v14
	v_ashrrev_i32_e32 v19, 31, v18
	v_ashrrev_i32_e32 v21, 31, v20
	v_ashrrev_i32_e32 v23, 31, v22
	v_ashrrev_i32_e32 v15, 31, v14
	v_lshlrev_b64 v[18:19], 12, v[18:19]
	v_lshlrev_b64 v[20:21], 12, v[20:21]
	v_lshlrev_b64 v[22:23], 12, v[22:23]
	v_ashrrev_i32_e32 v25, 31, v24
	v_ashrrev_i32_e32 v27, 31, v26
	v_ashrrev_i32_e32 v29, 31, v28
	v_ashrrev_i32_e32 v31, 31, v30
	v_lshlrev_b64 v[14:15], 12, v[14:15]
	v_lshl_add_u64 v[18:19], v[16:17], 0, v[18:19]
	v_lshl_add_u64 v[20:21], v[16:17], 0, v[20:21]
	v_lshl_add_u64 v[22:23], v[16:17], 0, v[22:23]
	v_lshlrev_b64 v[24:25], 12, v[24:25]
	v_lshlrev_b64 v[26:27], 12, v[26:27]
	v_lshlrev_b64 v[28:29], 12, v[28:29]
	v_lshlrev_b64 v[30:31], 12, v[30:31]
	v_lshl_add_u64 v[14:15], v[16:17], 0, v[14:15]
	v_lshl_add_u64 v[24:25], v[16:17], 0, v[24:25]
	v_lshl_add_u64 v[26:27], v[16:17], 0, v[26:27]
	v_lshl_add_u64 v[28:29], v[16:17], 0, v[28:29]
	v_lshl_add_u64 v[30:31], v[16:17], 0, v[30:31]
	global_load_dword v16, v[18:19], off nt
	global_load_dword v17, v[20:21], off nt
	s_nop 0
	global_load_dword v18, v[22:23], off nt
	global_load_dword v19, v[24:25], off nt
	global_load_dword v20, v[26:27], off nt
	global_load_dword v21, v[28:29], off nt
	s_nop 0
	global_load_dword v22, v[30:31], off nt
	s_nop 0
	global_load_dword v14, v[14:15], off nt
	s_waitcnt vmcnt(0)
	ds_write2_b32 v47, v0, v34 offset1:66
	ds_write2_b32 v47, v35, v36 offset0:132 offset1:198
	ds_write2_b32 v53, v37, v38 offset0:8 offset1:74
	ds_write2_b32 v53, v39, v40 offset0:140 offset1:206
	ds_write2_b32 v54, v41, v42 offset0:16 offset1:82
	ds_write2_b32 v54, v43, v44 offset0:148 offset1:214
	ds_write2_b32 v55, v45, v60 offset0:24 offset1:90
	ds_write2_b32 v55, v61, v62 offset0:156 offset1:222
	ds_write2_b32 v56, v63, v64 offset0:32 offset1:98
	ds_write2_b32 v56, v65, v66 offset0:164 offset1:230
	ds_write2_b32 v57, v67, v68 offset0:40 offset1:106
	ds_write2_b32 v57, v69, v32 offset0:172 offset1:238
	ds_write2_b32 v58, v16, v17 offset0:48 offset1:114
	ds_write2_b32 v58, v18, v19 offset0:180 offset1:246
	ds_write2_b32 v59, v20, v21 offset0:56 offset1:122
	ds_write2_b32 v59, v22, v14 offset0:188 offset1:254
	s_waitcnt lgkmcnt(0)
	ds_read2_b32 v[14:15], v49 offset1:33
	s_waitcnt lgkmcnt(0)
	v_cvt_pk_bf16_f32 v14, v14, v15
	ds_read2_b32 v[16:17], v49 offset0:66 offset1:99
	s_waitcnt lgkmcnt(0)
	v_cvt_pk_bf16_f32 v15, v16, v17
	ds_read2_b32 v[16:17], v49 offset0:132 offset1:165
	s_waitcnt lgkmcnt(0)
	v_cvt_pk_bf16_f32 v16, v16, v17
	ds_read2_b32 v[18:19], v49 offset0:198 offset1:231
	s_waitcnt lgkmcnt(0)
	v_cvt_pk_bf16_f32 v17, v18, v19
	v_add_u32_e32 v18, s26, v48
	s_ashr_i32 s39, s38, 31
	v_ashrrev_i32_e32 v19, 31, v18
	v_lshl_add_u64 v[20:21], s[38:39], 1, v[12:13]
	v_lshlrev_b64 v[24:25], 11, v[18:19]
	v_lshl_add_u64 v[24:25], v[20:21], 0, v[24:25]
	ds_read2_b32 v[22:23], v49 offset0:8 offset1:41
	global_store_dwordx4 v[24:25], v[14:17], off
	s_waitcnt lgkmcnt(0)
	s_nop 0
	v_cvt_pk_bf16_f32 v14, v22, v23
	ds_read2_b32 v[16:17], v49 offset0:74 offset1:107
	s_waitcnt lgkmcnt(0)
	v_cvt_pk_bf16_f32 v15, v16, v17
	ds_read2_b32 v[16:17], v49 offset0:140 offset1:173
	s_waitcnt lgkmcnt(0)
	v_cvt_pk_bf16_f32 v16, v16, v17
	ds_read2_b32 v[22:23], v49 offset0:206 offset1:239
	s_waitcnt lgkmcnt(0)
	v_cvt_pk_bf16_f32 v17, v22, v23
	v_add_u32_e32 v22, 8, v18
	v_ashrrev_i32_e32 v23, 31, v22
	v_lshlrev_b64 v[22:23], 11, v[22:23]
	v_lshl_add_u64 v[22:23], v[20:21], 0, v[22:23]
	ds_read2_b32 v[24:25], v49 offset0:16 offset1:49
	global_store_dwordx4 v[22:23], v[14:17], off
	s_waitcnt lgkmcnt(0)
	s_nop 0
	v_cvt_pk_bf16_f32 v14, v24, v25
	ds_read2_b32 v[16:17], v49 offset0:82 offset1:115
	s_waitcnt lgkmcnt(0)
	v_cvt_pk_bf16_f32 v15, v16, v17
	ds_read2_b32 v[16:17], v49 offset0:148 offset1:181
	s_waitcnt lgkmcnt(0)
	v_cvt_pk_bf16_f32 v16, v16, v17
	ds_read2_b32 v[22:23], v49 offset0:214 offset1:247
	s_waitcnt lgkmcnt(0)
	v_cvt_pk_bf16_f32 v17, v22, v23
	v_add_u32_e32 v22, 16, v18
	v_ashrrev_i32_e32 v23, 31, v22
	v_lshlrev_b64 v[22:23], 11, v[22:23]
	v_add_u32_e32 v18, 24, v18
	v_lshl_add_u64 v[22:23], v[20:21], 0, v[22:23]
	v_ashrrev_i32_e32 v19, 31, v18
	ds_read2_b32 v[24:25], v49 offset0:24 offset1:57
	global_store_dwordx4 v[22:23], v[14:17], off
	v_lshlrev_b64 v[18:19], 11, v[18:19]
	v_lshl_add_u64 v[18:19], v[20:21], 0, v[18:19]
	s_waitcnt lgkmcnt(0)
	v_cvt_pk_bf16_f32 v14, v24, v25
	ds_read2_b32 v[16:17], v49 offset0:90 offset1:123
	s_waitcnt lgkmcnt(0)
	v_cvt_pk_bf16_f32 v15, v16, v17
	ds_read2_b32 v[16:17], v49 offset0:156 offset1:189
	s_waitcnt lgkmcnt(0)
	v_cvt_pk_bf16_f32 v16, v16, v17
	ds_read2_b32 v[22:23], v49 offset0:222 offset1:255
	s_waitcnt lgkmcnt(0)
	v_cvt_pk_bf16_f32 v17, v22, v23
	global_store_dwordx4 v[18:19], v[14:17], off
	s_waitcnt lgkmcnt(0)
	s_branch .LBB0_134
